# attention: packed f32 adds for the softmax row sums (14 instead of 28 per tile), MFMA slots re-spaced
# baseline (speedup 1.0000x reference)
.Lat_qb:
	s_lshl_b32 s9, s2, 2
	s_lshr_b32 s10, s3, 1
	s_add_u32 s10, s10, s9
	s_add_u32 s11, s9, 3
	s_add_u32 s9, s9, 4
	s_lshl_b32 s18, s2, 8
	s_lshl_b32 s19, s3, 5
	s_add_u32 s18, s18, s19
	v_and_b32_e32 v235, 31, v186
	v_bfe_u32 v237, v186, 5, 1
	v_add_u32_e32 v235, s18, v235
	v_lshlrev_b32_e32 v219, 10, v235
	v_mul_u32_u24_e32 v236, 0x2cb0, v235
	v_lshl_add_u32 v220, v237, 4, v236
	v_lshl_add_u32 v197, v237, 3, v236
	global_load_dwordx4 v[102:105], v220, s[4:5] offset:0
	global_load_dwordx4 v[106:109], v220, s[4:5] offset:32
	global_load_dwordx4 v[110:113], v220, s[4:5] offset:64
	global_load_dwordx4 v[114:117], v220, s[4:5] offset:96
	s_mov_b64 s[12:13], s[4:5]
	s_add_i32 m0, s58, 0x0
	s_nop 0
	global_load_lds_dwordx4 v221, s[12:13]
	s_add_i32 m0, s58, 0x8000
	s_nop 0
	global_load_lds_dwordx4 v222, s[12:13]
	s_add_u32 s12, s12, 0xb2c00
	s_addc_u32 s13, s13, 0
	s_add_i32 m0, s58, 0x2000
	s_nop 0
	global_load_lds_dwordx4 v221, s[12:13]
	s_add_u32 s12, s12, 0xb2c00
	s_addc_u32 s13, s13, 0
	s_add_i32 m0, s58, 0x4000
	s_nop 0
	global_load_lds_dwordx4 v221, s[12:13]
	s_add_u32 s12, s12, 0xb2c00
	s_addc_u32 s13, s13, 0
	global_load_dwordx4 v[198:201], v219, s[6:7]
	s_add_i32 m0, s58, 0x6000
	s_nop 0
	global_load_lds_dwordx4 v221, s[12:13]
	s_add_u32 s14, s4, 0xb2c00
	s_addc_u32 s15, s5, 0
	s_add_i32 m0, s58, 0xa000
	s_nop 0
	global_load_lds_dwordx4 v222, s[14:15]
	v_mov_b32_e32 v230, 0xff800000
	v_mov_b32_e32 v231, 0
	v_mov_b32_e32 v0, 0
	v_mov_b32_e32 v1, 0
	v_mov_b32_e32 v2, 0
	v_mov_b32_e32 v3, 0
	v_mov_b32_e32 v4, 0
	v_mov_b32_e32 v5, 0
	v_mov_b32_e32 v6, 0
	v_mov_b32_e32 v7, 0
	v_mov_b32_e32 v8, 0
	v_mov_b32_e32 v9, 0
	v_mov_b32_e32 v10, 0
	v_mov_b32_e32 v11, 0
	v_mov_b32_e32 v12, 0
	v_mov_b32_e32 v13, 0
	v_mov_b32_e32 v14, 0
	v_mov_b32_e32 v15, 0
	v_mov_b32_e32 v16, 0
	v_mov_b32_e32 v17, 0
	v_mov_b32_e32 v18, 0
	v_mov_b32_e32 v19, 0
	v_mov_b32_e32 v20, 0
	v_mov_b32_e32 v21, 0
	v_mov_b32_e32 v22, 0
	v_mov_b32_e32 v23, 0
	v_mov_b32_e32 v24, 0
	v_mov_b32_e32 v25, 0
	v_mov_b32_e32 v26, 0
	v_mov_b32_e32 v27, 0
	v_mov_b32_e32 v28, 0
	v_mov_b32_e32 v29, 0
	v_mov_b32_e32 v30, 0
	v_mov_b32_e32 v31, 0
	s_waitcnt vmcnt(2)
	s_barrier
	ds_read_b128 v[118:121], v223 offset:0
	ds_read_b128 v[122:125], v223 offset:4096
	ds_read_b128 v[126:129], v224 offset:0
	ds_read_b128 v[130:133], v224 offset:4096
	ds_read_b128 v[134:137], v225 offset:0
	ds_read_b128 v[138:141], v225 offset:4096
	ds_read_b128 v[142:145], v226 offset:0
	ds_read_b128 v[146:149], v226 offset:4096
	s_waitcnt lgkmcnt(0)
	s_barrier
	v_mfma_f32_32x32x16_bf16 v[34:49], v[118:121], v[102:105], 0
	v_mfma_f32_32x32x16_bf16 v[50:65], v[122:125], v[102:105], 0
	v_mfma_f32_32x32x16_bf16 v[34:49], v[126:129], v[106:109], v[34:49]
	v_mfma_f32_32x32x16_bf16 v[50:65], v[130:133], v[106:109], v[50:65]
	v_mfma_f32_32x32x16_bf16 v[34:49], v[134:137], v[110:113], v[34:49]
	v_mfma_f32_32x32x16_bf16 v[50:65], v[138:141], v[110:113], v[50:65]
	v_mfma_f32_32x32x16_bf16 v[34:49], v[142:145], v[114:117], v[34:49]
	v_mfma_f32_32x32x16_bf16 v[50:65], v[146:149], v[114:117], v[50:65]
	ds_read_b128 v[118:121], v223 offset:8192
	ds_read_b128 v[122:125], v223 offset:12288
	ds_read_b128 v[126:129], v224 offset:8192
	ds_read_b128 v[130:133], v224 offset:12288
	ds_read_b128 v[134:137], v225 offset:8192
	ds_read_b128 v[138:141], v225 offset:12288
	ds_read_b128 v[142:145], v226 offset:8192
	ds_read_b128 v[146:149], v226 offset:12288
	s_waitcnt lgkmcnt(14)
	s_mov_b32 s8, 0
	s_nop 7
	v_lshrrev_b32_e32 v249, v229, v198
	v_lshrrev_b32_e32 v250, v229, v199
	v_bfe_i32 v235, v249, 0, 1
	v_bfe_i32 v236, v250, 0, 1
	v_bfe_i32 v237, v249, 1, 1
	v_bfe_i32 v238, v250, 1, 1
	v_bfe_i32 v239, v249, 2, 1
	v_bfe_i32 v240, v250, 2, 1
	v_bfe_i32 v241, v249, 3, 1
	v_bfe_i32 v242, v250, 3, 1
	v_bitop3_b32 v34, v34, s33, v235 bitop3:0xe4
	v_bitop3_b32 v50, v50, s33, v236 bitop3:0xe4
	v_bitop3_b32 v35, v35, s33, v237 bitop3:0xe4
	v_bitop3_b32 v51, v51, s33, v238 bitop3:0xe4
	v_bitop3_b32 v36, v36, s33, v239 bitop3:0xe4
	v_bitop3_b32 v52, v52, s33, v240 bitop3:0xe4
	v_bitop3_b32 v37, v37, s33, v241 bitop3:0xe4
	v_bitop3_b32 v53, v53, s33, v242 bitop3:0xe4
	v_max3_f32 v243, v34, s33, v50
	v_max3_f32 v248, v35, s33, v51
	v_max3_f32 v243, v243, v36, v52
	v_max3_f32 v248, v248, v37, v53
	v_bfe_i32 v235, v249, 8, 1
	v_bfe_i32 v236, v250, 8, 1
	v_bfe_i32 v237, v249, 9, 1
	v_bfe_i32 v238, v250, 9, 1
	v_bfe_i32 v239, v249, 10, 1
	v_bfe_i32 v240, v250, 10, 1
	v_bfe_i32 v241, v249, 11, 1
	v_bfe_i32 v242, v250, 11, 1
	v_bitop3_b32 v38, v38, s33, v235 bitop3:0xe4
	v_bitop3_b32 v54, v54, s33, v236 bitop3:0xe4
	v_bitop3_b32 v39, v39, s33, v237 bitop3:0xe4
	v_bitop3_b32 v55, v55, s33, v238 bitop3:0xe4
	v_bitop3_b32 v40, v40, s33, v239 bitop3:0xe4
	v_bitop3_b32 v56, v56, s33, v240 bitop3:0xe4
	v_bitop3_b32 v41, v41, s33, v241 bitop3:0xe4
	v_bitop3_b32 v57, v57, s33, v242 bitop3:0xe4
	v_max3_f32 v243, v243, v38, v54
	v_max3_f32 v248, v248, v39, v55
	v_max3_f32 v243, v243, v40, v56
	v_max3_f32 v248, v248, v41, v57
	v_bfe_i32 v235, v249, 16, 1
	v_bfe_i32 v236, v250, 16, 1
	v_bfe_i32 v237, v249, 17, 1
	v_bfe_i32 v238, v250, 17, 1
	v_bfe_i32 v239, v249, 18, 1
	v_bfe_i32 v240, v250, 18, 1
	v_bfe_i32 v241, v249, 19, 1
	v_bfe_i32 v242, v250, 19, 1
	v_bitop3_b32 v42, v42, s33, v235 bitop3:0xe4
	v_bitop3_b32 v58, v58, s33, v236 bitop3:0xe4
	v_bitop3_b32 v43, v43, s33, v237 bitop3:0xe4
	v_bitop3_b32 v59, v59, s33, v238 bitop3:0xe4
	v_bitop3_b32 v44, v44, s33, v239 bitop3:0xe4
	v_bitop3_b32 v60, v60, s33, v240 bitop3:0xe4
	v_bitop3_b32 v45, v45, s33, v241 bitop3:0xe4
	v_bitop3_b32 v61, v61, s33, v242 bitop3:0xe4
	v_max3_f32 v243, v243, v42, v58
	v_max3_f32 v248, v248, v43, v59
	v_max3_f32 v243, v243, v44, v60
	v_max3_f32 v248, v248, v45, v61
	v_bfe_i32 v235, v249, 24, 1
	v_bfe_i32 v236, v250, 24, 1
	v_bfe_i32 v237, v249, 25, 1
	v_bfe_i32 v238, v250, 25, 1
	v_bfe_i32 v239, v249, 26, 1
	v_bfe_i32 v240, v250, 26, 1
	v_bfe_i32 v241, v249, 27, 1
	v_bfe_i32 v242, v250, 27, 1
	v_bitop3_b32 v46, v46, s33, v235 bitop3:0xe4
	v_bitop3_b32 v62, v62, s33, v236 bitop3:0xe4
	v_bitop3_b32 v47, v47, s33, v237 bitop3:0xe4
	v_bitop3_b32 v63, v63, s33, v238 bitop3:0xe4
	v_bitop3_b32 v48, v48, s33, v239 bitop3:0xe4
	v_bitop3_b32 v64, v64, s33, v240 bitop3:0xe4
	v_bitop3_b32 v49, v49, s33, v241 bitop3:0xe4
	v_bitop3_b32 v65, v65, s33, v242 bitop3:0xe4
	v_max3_f32 v243, v243, v46, v62
	v_max3_f32 v248, v248, v47, v63
	v_max3_f32 v243, v243, v48, v64
	v_max3_f32 v248, v248, v49, v65
	v_max_f32_e32 v243, v243, v248
	v_mov_b32_e32 v248, v243
	s_nop 1
	v_permlane32_swap_b32_e32 v243, v248
	v_max3_f32 v243, v230, v243, v248
	v_cmp_neq_f32_e32 vcc, s33, v243
	s_nop 1
	v_cndmask_b32_e32 v248, 0, v243, vcc
	v_sub_f32_e32 v33, v230, v248
	v_mul_f32_e32 v33, 0x3e38aa3b, v33
	v_exp_f32_e32 v232, v33
	v_mul_f32_e32 v234, 0xbe38aa3b, v248
	v_mov_b32_e32 v230, v243

.Lat_nors_f0:
	v_fmamk_f32 v34, v34, 0x3e38aa3b, v234
	v_fmamk_f32 v35, v35, 0x3e38aa3b, v234
	s_waitcnt lgkmcnt(7)
	v_mfma_f32_32x32x16_bf16 v[70:85], v[118:121], v[102:105], 0
	ds_read_b64_tr_b16 v[154:155], v227 offset:0
	ds_read_b64_tr_b16 v[156:157], v227 offset:1024
	v_fmamk_f32 v36, v36, 0x3e38aa3b, v234
	v_fmamk_f32 v37, v37, 0x3e38aa3b, v234
	v_fmamk_f32 v38, v38, 0x3e38aa3b, v234
	v_fmamk_f32 v39, v39, 0x3e38aa3b, v234
	v_fmamk_f32 v40, v40, 0x3e38aa3b, v234
	v_fmamk_f32 v41, v41, 0x3e38aa3b, v234
	v_exp_f32_e32 v34, v34
	v_exp_f32_e32 v35, v35
	v_exp_f32_e32 v36, v36
	v_exp_f32_e32 v37, v37
	s_waitcnt lgkmcnt(8)
	v_mfma_f32_32x32x16_bf16 v[86:101], v[122:125], v[102:105], 0
	ds_read_b64_tr_b16 v[158:159], v228 offset:0
	ds_read_b64_tr_b16 v[160:161], v228 offset:1024
	v_exp_f32_e32 v38, v38
	v_exp_f32_e32 v39, v39
	v_exp_f32_e32 v40, v40
	v_exp_f32_e32 v41, v41
	v_pk_add_f32 v[244:245], v[34:35], v[38:39]
	v_pk_add_f32 v[246:247], v[36:37], v[40:41]
	v_cvt_pk_bf16_f32 v34, v34, v35
	v_cvt_pk_bf16_f32 v35, v36, v37
	v_cvt_pk_bf16_f32 v36, v38, v39
	v_cvt_pk_bf16_f32 v37, v40, v41
	v_fmamk_f32 v42, v42, 0x3e38aa3b, v234
	s_waitcnt lgkmcnt(9)
	v_mfma_f32_32x32x16_bf16 v[70:85], v[126:129], v[106:109], v[70:85]
	ds_read_b64_tr_b16 v[162:163], v227 offset:2048
	ds_read_b64_tr_b16 v[164:165], v227 offset:3072
	v_fmamk_f32 v43, v43, 0x3e38aa3b, v234
	v_fmamk_f32 v44, v44, 0x3e38aa3b, v234
	v_fmamk_f32 v45, v45, 0x3e38aa3b, v234
	v_fmamk_f32 v46, v46, 0x3e38aa3b, v234
	v_fmamk_f32 v47, v47, 0x3e38aa3b, v234
	v_fmamk_f32 v48, v48, 0x3e38aa3b, v234
	v_fmamk_f32 v49, v49, 0x3e38aa3b, v234
	v_exp_f32_e32 v42, v42
	v_exp_f32_e32 v43, v43
	v_exp_f32_e32 v44, v44
	s_waitcnt lgkmcnt(10)
	v_mfma_f32_32x32x16_bf16 v[86:101], v[130:133], v[106:109], v[86:101]
	ds_read_b64_tr_b16 v[166:167], v228 offset:2048
	ds_read_b64_tr_b16 v[168:169], v228 offset:3072
	v_exp_f32_e32 v45, v45
	v_exp_f32_e32 v46, v46
	v_exp_f32_e32 v47, v47
	v_exp_f32_e32 v48, v48
	v_exp_f32_e32 v49, v49
	v_pk_add_f32 v[244:245], v[244:245], v[42:43]
	v_pk_add_f32 v[246:247], v[246:247], v[44:45]
	v_pk_add_f32 v[244:245], v[244:245], v[46:47]
	v_pk_add_f32 v[246:247], v[246:247], v[48:49]
	v_cvt_pk_bf16_f32 v42, v42, v43
	v_cvt_pk_bf16_f32 v43, v44, v45
	s_waitcnt lgkmcnt(11)
	v_mfma_f32_32x32x16_bf16 v[70:85], v[134:137], v[110:113], v[70:85]
	ds_read_b64_tr_b16 v[170:171], v227 offset:4096
	ds_read_b64_tr_b16 v[172:173], v227 offset:5120
	v_cvt_pk_bf16_f32 v44, v46, v47
	v_cvt_pk_bf16_f32 v45, v48, v49
	v_fmamk_f32 v50, v50, 0x3e38aa3b, v234
	v_fmamk_f32 v51, v51, 0x3e38aa3b, v234
	v_fmamk_f32 v52, v52, 0x3e38aa3b, v234
	v_fmamk_f32 v53, v53, 0x3e38aa3b, v234
	v_fmamk_f32 v54, v54, 0x3e38aa3b, v234
	v_fmamk_f32 v55, v55, 0x3e38aa3b, v234
	v_fmamk_f32 v56, v56, 0x3e38aa3b, v234
	v_fmamk_f32 v57, v57, 0x3e38aa3b, v234
	s_waitcnt lgkmcnt(12)
	v_mfma_f32_32x32x16_bf16 v[86:101], v[138:141], v[110:113], v[86:101]
	ds_read_b64_tr_b16 v[174:175], v228 offset:4096
	ds_read_b64_tr_b16 v[176:177], v228 offset:5120
	v_exp_f32_e32 v50, v50
	v_exp_f32_e32 v51, v51
	v_exp_f32_e32 v52, v52
	v_exp_f32_e32 v53, v53
	v_exp_f32_e32 v54, v54
	v_exp_f32_e32 v55, v55
	v_exp_f32_e32 v56, v56
	v_exp_f32_e32 v57, v57
	v_pk_add_f32 v[244:245], v[244:245], v[50:51]
	v_pk_add_f32 v[246:247], v[246:247], v[52:53]
	v_pk_add_f32 v[244:245], v[244:245], v[54:55]
	s_waitcnt lgkmcnt(13)
	v_mfma_f32_32x32x16_bf16 v[70:85], v[142:145], v[114:117], v[70:85]
	ds_read_b64_tr_b16 v[178:179], v227 offset:6144
	ds_read_b64_tr_b16 v[180:181], v227 offset:7168
	v_pk_add_f32 v[246:247], v[246:247], v[56:57]
	v_cvt_pk_bf16_f32 v50, v50, v51
	v_cvt_pk_bf16_f32 v51, v52, v53
	v_cvt_pk_bf16_f32 v52, v54, v55
	v_cvt_pk_bf16_f32 v53, v56, v57
	v_fmamk_f32 v58, v58, 0x3e38aa3b, v234
	v_fmamk_f32 v59, v59, 0x3e38aa3b, v234
	v_fmamk_f32 v60, v60, 0x3e38aa3b, v234
	v_fmamk_f32 v61, v61, 0x3e38aa3b, v234
	v_fmamk_f32 v62, v62, 0x3e38aa3b, v234
	s_waitcnt lgkmcnt(14)
	v_mfma_f32_32x32x16_bf16 v[86:101], v[146:149], v[114:117], v[86:101]
	ds_read_b64_tr_b16 v[182:183], v228 offset:6144
	ds_read_b64_tr_b16 v[184:185], v228 offset:7168
	s_waitcnt lgkmcnt(14)
	v_fmamk_f32 v63, v63, 0x3e38aa3b, v234
	v_fmamk_f32 v64, v64, 0x3e38aa3b, v234
	v_fmamk_f32 v65, v65, 0x3e38aa3b, v234
	v_exp_f32_e32 v58, v58
	v_exp_f32_e32 v59, v59
	v_exp_f32_e32 v60, v60
	v_exp_f32_e32 v61, v61
	v_exp_f32_e32 v62, v62
	v_exp_f32_e32 v63, v63
	v_exp_f32_e32 v64, v64
	v_exp_f32_e32 v65, v65
	v_pk_add_f32 v[244:245], v[244:245], v[58:59]
	v_pk_add_f32 v[246:247], v[246:247], v[60:61]
	s_waitcnt lgkmcnt(14)
	v_mfma_f32_32x32x16_bf16 v[0:15], v[154:157], v[34:37], v[0:15]
	ds_read_b128 v[118:121], v223 offset:16384
	v_pk_add_f32 v[244:245], v[244:245], v[62:63]
	v_pk_add_f32 v[246:247], v[246:247], v[64:65]
	v_cvt_pk_bf16_f32 v58, v58, v59
	v_cvt_pk_bf16_f32 v59, v60, v61
	v_cvt_pk_bf16_f32 v60, v62, v63
	v_cvt_pk_bf16_f32 v61, v64, v65
	v_add_f32_e32 v244, v244, v245
	v_add_f32_e32 v246, v246, v247
	v_add_f32_e32 v244, v244, v246
	v_fma_f32 v231, v231, v232, v244
	v_lshrrev_b32_e32 v249, v229, v200
	s_waitcnt lgkmcnt(13)
	v_mfma_f32_32x32x16_bf16 v[16:31], v[158:161], v[34:37], v[16:31]
	ds_read_b128 v[122:125], v223 offset:20480
	v_lshrrev_b32_e32 v250, v229, v201
	v_bfe_i32 v235, v249, 0, 1
	v_bfe_i32 v236, v250, 0, 1
	v_bfe_i32 v237, v249, 1, 1
	v_bfe_i32 v238, v250, 1, 1
	v_bfe_i32 v239, v249, 2, 1
	v_bfe_i32 v240, v250, 2, 1
	v_bfe_i32 v241, v249, 3, 1
	v_bfe_i32 v242, v250, 3, 1
	v_bitop3_b32 v70, v70, s33, v235 bitop3:0xe4
	v_bitop3_b32 v86, v86, s33, v236 bitop3:0xe4
	v_bitop3_b32 v71, v71, s33, v237 bitop3:0xe4
	s_waitcnt lgkmcnt(12)
	v_mfma_f32_32x32x16_bf16 v[0:15], v[162:165], v[42:45], v[0:15]
	ds_read_b128 v[126:129], v224 offset:16384
	v_bitop3_b32 v87, v87, s33, v238 bitop3:0xe4
	v_bitop3_b32 v72, v72, s33, v239 bitop3:0xe4
	v_bitop3_b32 v88, v88, s33, v240 bitop3:0xe4
	v_bitop3_b32 v73, v73, s33, v241 bitop3:0xe4
	v_bitop3_b32 v89, v89, s33, v242 bitop3:0xe4
	v_max3_f32 v243, v70, s33, v86
	v_max3_f32 v248, v71, s33, v87
	v_max3_f32 v243, v243, v72, v88
	v_max3_f32 v248, v248, v73, v89
	v_bfe_i32 v235, v249, 8, 1
	v_bfe_i32 v236, v250, 8, 1
	v_bfe_i32 v237, v249, 9, 1
	s_waitcnt lgkmcnt(11)
	v_mfma_f32_32x32x16_bf16 v[16:31], v[166:169], v[42:45], v[16:31]
	ds_read_b128 v[130:133], v224 offset:20480
	v_bfe_i32 v238, v250, 9, 1
	v_bfe_i32 v239, v249, 10, 1
	v_bfe_i32 v240, v250, 10, 1
	v_bfe_i32 v241, v249, 11, 1
	v_bfe_i32 v242, v250, 11, 1
	v_bitop3_b32 v74, v74, s33, v235 bitop3:0xe4
	v_bitop3_b32 v90, v90, s33, v236 bitop3:0xe4
	v_bitop3_b32 v75, v75, s33, v237 bitop3:0xe4
	v_bitop3_b32 v91, v91, s33, v238 bitop3:0xe4
	v_bitop3_b32 v76, v76, s33, v239 bitop3:0xe4
	v_bitop3_b32 v92, v92, s33, v240 bitop3:0xe4
	v_bitop3_b32 v77, v77, s33, v241 bitop3:0xe4
	s_waitcnt lgkmcnt(10)
	v_mfma_f32_32x32x16_bf16 v[0:15], v[170:173], v[50:53], v[0:15]
	ds_read_b128 v[134:137], v225 offset:16384
	v_bitop3_b32 v93, v93, s33, v242 bitop3:0xe4
	v_max3_f32 v243, v243, v74, v90
	v_max3_f32 v248, v248, v75, v91
	v_max3_f32 v243, v243, v76, v92
	v_max3_f32 v248, v248, v77, v93
	v_bfe_i32 v235, v249, 16, 1
	v_bfe_i32 v236, v250, 16, 1
	v_bfe_i32 v237, v249, 17, 1
	v_bfe_i32 v238, v250, 17, 1
	v_bfe_i32 v239, v249, 18, 1
	v_bfe_i32 v240, v250, 18, 1
	v_bfe_i32 v241, v249, 19, 1
	s_waitcnt lgkmcnt(9)
	v_mfma_f32_32x32x16_bf16 v[16:31], v[174:177], v[50:53], v[16:31]
	ds_read_b128 v[138:141], v225 offset:20480
	v_bfe_i32 v242, v250, 19, 1
	v_bitop3_b32 v78, v78, s33, v235 bitop3:0xe4
	v_bitop3_b32 v94, v94, s33, v236 bitop3:0xe4
	v_bitop3_b32 v79, v79, s33, v237 bitop3:0xe4
	v_bitop3_b32 v95, v95, s33, v238 bitop3:0xe4
	v_bitop3_b32 v80, v80, s33, v239 bitop3:0xe4
	v_bitop3_b32 v96, v96, s33, v240 bitop3:0xe4
	v_bitop3_b32 v81, v81, s33, v241 bitop3:0xe4
	v_bitop3_b32 v97, v97, s33, v242 bitop3:0xe4
	v_max3_f32 v243, v243, v78, v94
	v_max3_f32 v248, v248, v79, v95
	v_max3_f32 v243, v243, v80, v96
	s_waitcnt lgkmcnt(8)
	v_mfma_f32_32x32x16_bf16 v[0:15], v[178:181], v[58:61], v[0:15]
	ds_read_b128 v[142:145], v226 offset:16384
	v_max3_f32 v248, v248, v81, v97
	v_bfe_i32 v235, v249, 24, 1
	v_bfe_i32 v236, v250, 24, 1
	v_bfe_i32 v237, v249, 25, 1
	v_bfe_i32 v238, v250, 25, 1
	v_bfe_i32 v239, v249, 26, 1
	v_bfe_i32 v240, v250, 26, 1
	v_bfe_i32 v241, v249, 27, 1
	v_bfe_i32 v242, v250, 27, 1
	v_bitop3_b32 v82, v82, s33, v235 bitop3:0xe4
	v_bitop3_b32 v98, v98, s33, v236 bitop3:0xe4
	v_bitop3_b32 v83, v83, s33, v237 bitop3:0xe4
	s_waitcnt lgkmcnt(7)
	v_mfma_f32_32x32x16_bf16 v[16:31], v[182:185], v[58:61], v[16:31]
	ds_read_b128 v[146:149], v226 offset:20480
	v_bitop3_b32 v99, v99, s33, v238 bitop3:0xe4
	v_bitop3_b32 v84, v84, s33, v239 bitop3:0xe4
	v_bitop3_b32 v100, v100, s33, v240 bitop3:0xe4
	v_bitop3_b32 v85, v85, s33, v241 bitop3:0xe4
	v_bitop3_b32 v101, v101, s33, v242 bitop3:0xe4
	v_max3_f32 v243, v243, v82, v98
	v_max3_f32 v248, v248, v83, v99
	v_max3_f32 v243, v243, v84, v100
	v_max3_f32 v248, v248, v85, v101
	v_max_f32_e32 v243, v243, v248
	v_mov_b32_e32 v248, v243
	s_nop 1
	v_permlane32_swap_b32_e32 v243, v248
	v_max3_f32 v243, v230, v243, v248
	v_cmp_neq_f32_e32 vcc, s33, v243
	s_nop 1
	v_cndmask_b32_e32 v248, 0, v243, vcc
	v_sub_f32_e32 v33, v230, v248
	v_mul_f32_e32 v33, 0x3e38aa3b, v33
	v_exp_f32_e32 v232, v33
	v_mul_f32_e32 v234, 0xbe38aa3b, v248
	v_mov_b32_e32 v230, v243
	s_waitcnt vmcnt(3)
	s_barrier
	s_add_u32 s8, s8, 1
	s_cmp_lt_u32 s8, s9
	s_cbranch_scc1 .Lat_loop_1
	s_branch .Lat_epilogue

.Lat_nors_l0:
	v_fmamk_f32 v34, v34, 0x3e38aa3b, v234
	v_fmamk_f32 v35, v35, 0x3e38aa3b, v234
	v_fmamk_f32 v36, v36, 0x3e38aa3b, v234
	ds_read_b64_tr_b16 v[168:169], v228 offset:3072
	s_waitcnt lgkmcnt(14)
	v_fmamk_f32 v37, v37, 0x3e38aa3b, v234
	v_fmamk_f32 v38, v38, 0x3e38aa3b, v234
	v_fmamk_f32 v39, v39, 0x3e38aa3b, v234
	ds_read_b64_tr_b16 v[170:171], v227 offset:4096
	s_waitcnt lgkmcnt(14)
	v_fmamk_f32 v40, v40, 0x3e38aa3b, v234
	v_fmamk_f32 v41, v41, 0x3e38aa3b, v234
	v_exp_f32_e32 v34, v34
	ds_read_b64_tr_b16 v[172:173], v227 offset:5120
	s_waitcnt lgkmcnt(14)
	v_exp_f32_e32 v35, v35
	v_exp_f32_e32 v36, v36
	v_exp_f32_e32 v37, v37
	ds_read_b64_tr_b16 v[174:175], v228 offset:4096
	s_waitcnt lgkmcnt(14)
	v_exp_f32_e32 v38, v38
	v_exp_f32_e32 v39, v39
	v_exp_f32_e32 v40, v40
	ds_read_b64_tr_b16 v[176:177], v228 offset:5120
	s_waitcnt lgkmcnt(14)
	v_exp_f32_e32 v41, v41
	v_pk_add_f32 v[244:245], v[34:35], v[38:39]
	v_pk_add_f32 v[246:247], v[36:37], v[40:41]
	ds_read_b64_tr_b16 v[178:179], v227 offset:6144
	s_waitcnt lgkmcnt(14)
	v_cvt_pk_bf16_f32 v34, v34, v35
	v_cvt_pk_bf16_f32 v35, v36, v37
	v_cvt_pk_bf16_f32 v36, v38, v39
	ds_read_b64_tr_b16 v[180:181], v227 offset:7168
	s_waitcnt lgkmcnt(14)
	v_cvt_pk_bf16_f32 v37, v40, v41
	s_waitcnt lgkmcnt(12)
	v_mfma_f32_32x32x16_bf16 v[0:15], v[154:157], v[34:37], v[0:15]
	s_waitcnt lgkmcnt(10)
	v_mfma_f32_32x32x16_bf16 v[16:31], v[158:161], v[34:37], v[16:31]
	v_fmamk_f32 v42, v42, 0x3e38aa3b, v234
	v_fmamk_f32 v43, v43, 0x3e38aa3b, v234
	v_fmamk_f32 v44, v44, 0x3e38aa3b, v234
	ds_read_b64_tr_b16 v[182:183], v228 offset:6144
	v_fmamk_f32 v45, v45, 0x3e38aa3b, v234
	v_fmamk_f32 v46, v46, 0x3e38aa3b, v234
	v_fmamk_f32 v47, v47, 0x3e38aa3b, v234
	ds_read_b64_tr_b16 v[184:185], v228 offset:7168
	v_fmamk_f32 v48, v48, 0x3e38aa3b, v234
	v_fmamk_f32 v49, v49, 0x3e38aa3b, v234
	v_exp_f32_e32 v42, v42
	v_exp_f32_e32 v43, v43
	v_exp_f32_e32 v44, v44
	v_exp_f32_e32 v45, v45
	v_exp_f32_e32 v46, v46
	v_exp_f32_e32 v47, v47
	v_exp_f32_e32 v48, v48
	v_exp_f32_e32 v49, v49
	v_pk_add_f32 v[244:245], v[244:245], v[42:43]
	v_pk_add_f32 v[246:247], v[246:247], v[44:45]
	v_pk_add_f32 v[244:245], v[244:245], v[46:47]
	v_pk_add_f32 v[246:247], v[246:247], v[48:49]
	v_cvt_pk_bf16_f32 v42, v42, v43
	v_cvt_pk_bf16_f32 v43, v44, v45
	v_cvt_pk_bf16_f32 v44, v46, v47
	v_cvt_pk_bf16_f32 v45, v48, v49
	s_waitcnt lgkmcnt(10)
	v_mfma_f32_32x32x16_bf16 v[0:15], v[162:165], v[42:45], v[0:15]
	s_waitcnt lgkmcnt(8)
	v_mfma_f32_32x32x16_bf16 v[16:31], v[166:169], v[42:45], v[16:31]
	v_fmamk_f32 v50, v50, 0x3e38aa3b, v234
	v_fmamk_f32 v51, v51, 0x3e38aa3b, v234
	v_fmamk_f32 v52, v52, 0x3e38aa3b, v234
	v_fmamk_f32 v53, v53, 0x3e38aa3b, v234
	v_fmamk_f32 v54, v54, 0x3e38aa3b, v234
	v_fmamk_f32 v55, v55, 0x3e38aa3b, v234
	v_fmamk_f32 v56, v56, 0x3e38aa3b, v234
	v_fmamk_f32 v57, v57, 0x3e38aa3b, v234
	v_exp_f32_e32 v50, v50
	v_exp_f32_e32 v51, v51
	v_exp_f32_e32 v52, v52
	v_exp_f32_e32 v53, v53
	v_exp_f32_e32 v54, v54
	v_exp_f32_e32 v55, v55
	v_exp_f32_e32 v56, v56
	v_exp_f32_e32 v57, v57
	v_pk_add_f32 v[244:245], v[244:245], v[50:51]
	v_pk_add_f32 v[246:247], v[246:247], v[52:53]
	v_pk_add_f32 v[244:245], v[244:245], v[54:55]
	v_pk_add_f32 v[246:247], v[246:247], v[56:57]
	v_cvt_pk_bf16_f32 v50, v50, v51
	v_cvt_pk_bf16_f32 v51, v52, v53
	v_cvt_pk_bf16_f32 v52, v54, v55
	v_cvt_pk_bf16_f32 v53, v56, v57
	s_waitcnt lgkmcnt(6)
	v_mfma_f32_32x32x16_bf16 v[0:15], v[170:173], v[50:53], v[0:15]
	s_waitcnt lgkmcnt(4)
	v_mfma_f32_32x32x16_bf16 v[16:31], v[174:177], v[50:53], v[16:31]
	v_fmamk_f32 v58, v58, 0x3e38aa3b, v234
	v_fmamk_f32 v59, v59, 0x3e38aa3b, v234
	v_fmamk_f32 v60, v60, 0x3e38aa3b, v234
	v_fmamk_f32 v61, v61, 0x3e38aa3b, v234
	v_fmamk_f32 v62, v62, 0x3e38aa3b, v234
	v_fmamk_f32 v63, v63, 0x3e38aa3b, v234
	v_fmamk_f32 v64, v64, 0x3e38aa3b, v234
	v_fmamk_f32 v65, v65, 0x3e38aa3b, v234
	v_exp_f32_e32 v58, v58
	v_exp_f32_e32 v59, v59
	v_exp_f32_e32 v60, v60
	v_exp_f32_e32 v61, v61
	v_exp_f32_e32 v62, v62
	v_exp_f32_e32 v63, v63
	v_exp_f32_e32 v64, v64
	v_exp_f32_e32 v65, v65
	v_pk_add_f32 v[244:245], v[244:245], v[58:59]
	v_pk_add_f32 v[246:247], v[246:247], v[60:61]
	v_pk_add_f32 v[244:245], v[244:245], v[62:63]
	v_pk_add_f32 v[246:247], v[246:247], v[64:65]
	v_cvt_pk_bf16_f32 v58, v58, v59
	v_cvt_pk_bf16_f32 v59, v60, v61
	v_cvt_pk_bf16_f32 v60, v62, v63
	v_cvt_pk_bf16_f32 v61, v64, v65
	v_add_f32_e32 v244, v244, v245
	v_add_f32_e32 v246, v246, v247
	v_add_f32_e32 v244, v244, v246
	v_fma_f32 v231, v231, v232, v244
	s_waitcnt lgkmcnt(2)
	v_mfma_f32_32x32x16_bf16 v[0:15], v[178:181], v[58:61], v[0:15]
	s_waitcnt lgkmcnt(0)
	v_mfma_f32_32x32x16_bf16 v[16:31], v[182:185], v[58:61], v[16:31]
	s_waitcnt vmcnt(3)
	s_barrier
	s_add_u32 s8, s8, 1
	s_cmp_lt_u32 s8, s9
	s_cbranch_scc1 .Lat_loop_1
	s_branch .Lat_epilogue

.Lat_nors_f1:
	v_fmamk_f32 v70, v70, 0x3e38aa3b, v234
	v_fmamk_f32 v71, v71, 0x3e38aa3b, v234
	s_waitcnt lgkmcnt(7)
	v_mfma_f32_32x32x16_bf16 v[34:49], v[118:121], v[102:105], 0
	ds_read_b64_tr_b16 v[154:155], v227 offset:8192
	ds_read_b64_tr_b16 v[156:157], v227 offset:9216
	v_fmamk_f32 v72, v72, 0x3e38aa3b, v234
	v_fmamk_f32 v73, v73, 0x3e38aa3b, v234
	v_fmamk_f32 v74, v74, 0x3e38aa3b, v234
	v_fmamk_f32 v75, v75, 0x3e38aa3b, v234
	v_fmamk_f32 v76, v76, 0x3e38aa3b, v234
	v_fmamk_f32 v77, v77, 0x3e38aa3b, v234
	v_exp_f32_e32 v70, v70
	v_exp_f32_e32 v71, v71
	v_exp_f32_e32 v72, v72
	v_exp_f32_e32 v73, v73
	s_waitcnt lgkmcnt(8)
	v_mfma_f32_32x32x16_bf16 v[50:65], v[122:125], v[102:105], 0
	ds_read_b64_tr_b16 v[158:159], v228 offset:8192
	ds_read_b64_tr_b16 v[160:161], v228 offset:9216
	v_exp_f32_e32 v74, v74
	v_exp_f32_e32 v75, v75
	v_exp_f32_e32 v76, v76
	v_exp_f32_e32 v77, v77
	v_pk_add_f32 v[244:245], v[70:71], v[74:75]
	v_pk_add_f32 v[246:247], v[72:73], v[76:77]
	v_cvt_pk_bf16_f32 v70, v70, v71
	v_cvt_pk_bf16_f32 v71, v72, v73
	v_cvt_pk_bf16_f32 v72, v74, v75
	v_cvt_pk_bf16_f32 v73, v76, v77
	v_fmamk_f32 v78, v78, 0x3e38aa3b, v234
	s_waitcnt lgkmcnt(9)
	v_mfma_f32_32x32x16_bf16 v[34:49], v[126:129], v[106:109], v[34:49]
	ds_read_b64_tr_b16 v[162:163], v227 offset:10240
	ds_read_b64_tr_b16 v[164:165], v227 offset:11264
	v_fmamk_f32 v79, v79, 0x3e38aa3b, v234
	v_fmamk_f32 v80, v80, 0x3e38aa3b, v234
	v_fmamk_f32 v81, v81, 0x3e38aa3b, v234
	v_fmamk_f32 v82, v82, 0x3e38aa3b, v234
	v_fmamk_f32 v83, v83, 0x3e38aa3b, v234
	v_fmamk_f32 v84, v84, 0x3e38aa3b, v234
	v_fmamk_f32 v85, v85, 0x3e38aa3b, v234
	v_exp_f32_e32 v78, v78
	v_exp_f32_e32 v79, v79
	v_exp_f32_e32 v80, v80
	s_waitcnt lgkmcnt(10)
	v_mfma_f32_32x32x16_bf16 v[50:65], v[130:133], v[106:109], v[50:65]
	ds_read_b64_tr_b16 v[166:167], v228 offset:10240
	ds_read_b64_tr_b16 v[168:169], v228 offset:11264
	v_exp_f32_e32 v81, v81
	v_exp_f32_e32 v82, v82
	v_exp_f32_e32 v83, v83
	v_exp_f32_e32 v84, v84
	v_exp_f32_e32 v85, v85
	v_pk_add_f32 v[244:245], v[244:245], v[78:79]
	v_pk_add_f32 v[246:247], v[246:247], v[80:81]
	v_pk_add_f32 v[244:245], v[244:245], v[82:83]
	v_pk_add_f32 v[246:247], v[246:247], v[84:85]
	v_cvt_pk_bf16_f32 v78, v78, v79
	v_cvt_pk_bf16_f32 v79, v80, v81
	s_waitcnt lgkmcnt(11)
	v_mfma_f32_32x32x16_bf16 v[34:49], v[134:137], v[110:113], v[34:49]
	ds_read_b64_tr_b16 v[170:171], v227 offset:12288
	ds_read_b64_tr_b16 v[172:173], v227 offset:13312
	v_cvt_pk_bf16_f32 v80, v82, v83
	v_cvt_pk_bf16_f32 v81, v84, v85
	v_fmamk_f32 v86, v86, 0x3e38aa3b, v234
	v_fmamk_f32 v87, v87, 0x3e38aa3b, v234
	v_fmamk_f32 v88, v88, 0x3e38aa3b, v234
	v_fmamk_f32 v89, v89, 0x3e38aa3b, v234
	v_fmamk_f32 v90, v90, 0x3e38aa3b, v234
	v_fmamk_f32 v91, v91, 0x3e38aa3b, v234
	v_fmamk_f32 v92, v92, 0x3e38aa3b, v234
	v_fmamk_f32 v93, v93, 0x3e38aa3b, v234
	s_waitcnt lgkmcnt(12)
	v_mfma_f32_32x32x16_bf16 v[50:65], v[138:141], v[110:113], v[50:65]
	ds_read_b64_tr_b16 v[174:175], v228 offset:12288
	ds_read_b64_tr_b16 v[176:177], v228 offset:13312
	v_exp_f32_e32 v86, v86
	v_exp_f32_e32 v87, v87
	v_exp_f32_e32 v88, v88
	v_exp_f32_e32 v89, v89
	v_exp_f32_e32 v90, v90
	v_exp_f32_e32 v91, v91
	v_exp_f32_e32 v92, v92
	v_exp_f32_e32 v93, v93
	v_pk_add_f32 v[244:245], v[244:245], v[86:87]
	v_pk_add_f32 v[246:247], v[246:247], v[88:89]
	v_pk_add_f32 v[244:245], v[244:245], v[90:91]
	s_waitcnt lgkmcnt(13)
	v_mfma_f32_32x32x16_bf16 v[34:49], v[142:145], v[114:117], v[34:49]
	ds_read_b64_tr_b16 v[178:179], v227 offset:14336
	ds_read_b64_tr_b16 v[180:181], v227 offset:15360
	v_pk_add_f32 v[246:247], v[246:247], v[92:93]
	v_cvt_pk_bf16_f32 v86, v86, v87
	v_cvt_pk_bf16_f32 v87, v88, v89
	v_cvt_pk_bf16_f32 v88, v90, v91
	v_cvt_pk_bf16_f32 v89, v92, v93
	v_fmamk_f32 v94, v94, 0x3e38aa3b, v234
	v_fmamk_f32 v95, v95, 0x3e38aa3b, v234
	v_fmamk_f32 v96, v96, 0x3e38aa3b, v234
	v_fmamk_f32 v97, v97, 0x3e38aa3b, v234
	v_fmamk_f32 v98, v98, 0x3e38aa3b, v234
	s_waitcnt lgkmcnt(14)
	v_mfma_f32_32x32x16_bf16 v[50:65], v[146:149], v[114:117], v[50:65]
	ds_read_b64_tr_b16 v[182:183], v228 offset:14336
	ds_read_b64_tr_b16 v[184:185], v228 offset:15360
	s_waitcnt lgkmcnt(14)
	v_fmamk_f32 v99, v99, 0x3e38aa3b, v234
	v_fmamk_f32 v100, v100, 0x3e38aa3b, v234
	v_fmamk_f32 v101, v101, 0x3e38aa3b, v234
	v_exp_f32_e32 v94, v94
	v_exp_f32_e32 v95, v95
	v_exp_f32_e32 v96, v96
	v_exp_f32_e32 v97, v97
	v_exp_f32_e32 v98, v98
	v_exp_f32_e32 v99, v99
	v_exp_f32_e32 v100, v100
	v_exp_f32_e32 v101, v101
	v_pk_add_f32 v[244:245], v[244:245], v[94:95]
	v_pk_add_f32 v[246:247], v[246:247], v[96:97]
	s_waitcnt lgkmcnt(14)
	v_mfma_f32_32x32x16_bf16 v[0:15], v[154:157], v[70:73], v[0:15]
	ds_read_b128 v[118:121], v223 offset:24576
	v_pk_add_f32 v[244:245], v[244:245], v[98:99]
	v_pk_add_f32 v[246:247], v[246:247], v[100:101]
	v_cvt_pk_bf16_f32 v94, v94, v95
	v_cvt_pk_bf16_f32 v95, v96, v97
	v_cvt_pk_bf16_f32 v96, v98, v99
	v_cvt_pk_bf16_f32 v97, v100, v101
	v_add_f32_e32 v244, v244, v245
	v_add_f32_e32 v246, v246, v247
	v_add_f32_e32 v244, v244, v246
	v_fma_f32 v231, v231, v232, v244
	s_waitcnt vmcnt(4)
	v_lshrrev_b32_e32 v249, v229, v202
	s_waitcnt lgkmcnt(13)
	v_mfma_f32_32x32x16_bf16 v[16:31], v[158:161], v[70:73], v[16:31]
	ds_read_b128 v[122:125], v223 offset:28672
	v_lshrrev_b32_e32 v250, v229, v203
	v_bfe_i32 v235, v249, 0, 1
	v_bfe_i32 v236, v250, 0, 1
	v_bfe_i32 v237, v249, 1, 1
	v_bfe_i32 v238, v250, 1, 1
	v_bfe_i32 v239, v249, 2, 1
	v_bfe_i32 v240, v250, 2, 1
	v_bfe_i32 v241, v249, 3, 1
	v_bfe_i32 v242, v250, 3, 1
	v_bitop3_b32 v34, v34, s33, v235 bitop3:0xe4
	v_bitop3_b32 v50, v50, s33, v236 bitop3:0xe4
	v_bitop3_b32 v35, v35, s33, v237 bitop3:0xe4
	s_waitcnt lgkmcnt(12)
	v_mfma_f32_32x32x16_bf16 v[0:15], v[162:165], v[78:81], v[0:15]
	ds_read_b128 v[126:129], v224 offset:24576
	v_bitop3_b32 v51, v51, s33, v238 bitop3:0xe4
	v_bitop3_b32 v36, v36, s33, v239 bitop3:0xe4
	v_bitop3_b32 v52, v52, s33, v240 bitop3:0xe4
	v_bitop3_b32 v37, v37, s33, v241 bitop3:0xe4
	v_bitop3_b32 v53, v53, s33, v242 bitop3:0xe4
	v_max3_f32 v243, v34, s33, v50
	v_max3_f32 v248, v35, s33, v51
	v_max3_f32 v243, v243, v36, v52
	v_max3_f32 v248, v248, v37, v53
	v_bfe_i32 v235, v249, 8, 1
	v_bfe_i32 v236, v250, 8, 1
	v_bfe_i32 v237, v249, 9, 1
	s_waitcnt lgkmcnt(11)
	v_mfma_f32_32x32x16_bf16 v[16:31], v[166:169], v[78:81], v[16:31]
	ds_read_b128 v[130:133], v224 offset:28672
	v_bfe_i32 v238, v250, 9, 1
	v_bfe_i32 v239, v249, 10, 1
	v_bfe_i32 v240, v250, 10, 1
	v_bfe_i32 v241, v249, 11, 1
	v_bfe_i32 v242, v250, 11, 1
	v_bitop3_b32 v38, v38, s33, v235 bitop3:0xe4
	v_bitop3_b32 v54, v54, s33, v236 bitop3:0xe4
	v_bitop3_b32 v39, v39, s33, v237 bitop3:0xe4
	v_bitop3_b32 v55, v55, s33, v238 bitop3:0xe4
	v_bitop3_b32 v40, v40, s33, v239 bitop3:0xe4
	v_bitop3_b32 v56, v56, s33, v240 bitop3:0xe4
	v_bitop3_b32 v41, v41, s33, v241 bitop3:0xe4
	s_waitcnt lgkmcnt(10)
	v_mfma_f32_32x32x16_bf16 v[0:15], v[170:173], v[86:89], v[0:15]
	ds_read_b128 v[134:137], v225 offset:24576
	v_bitop3_b32 v57, v57, s33, v242 bitop3:0xe4
	v_max3_f32 v243, v243, v38, v54
	v_max3_f32 v248, v248, v39, v55
	v_max3_f32 v243, v243, v40, v56
	v_max3_f32 v248, v248, v41, v57
	v_bfe_i32 v235, v249, 16, 1
	v_bfe_i32 v236, v250, 16, 1
	v_bfe_i32 v237, v249, 17, 1
	v_bfe_i32 v238, v250, 17, 1
	v_bfe_i32 v239, v249, 18, 1
	v_bfe_i32 v240, v250, 18, 1
	v_bfe_i32 v241, v249, 19, 1
	s_waitcnt lgkmcnt(9)
	v_mfma_f32_32x32x16_bf16 v[16:31], v[174:177], v[86:89], v[16:31]
	ds_read_b128 v[138:141], v225 offset:28672
	v_bfe_i32 v242, v250, 19, 1
	v_bitop3_b32 v42, v42, s33, v235 bitop3:0xe4
	v_bitop3_b32 v58, v58, s33, v236 bitop3:0xe4
	v_bitop3_b32 v43, v43, s33, v237 bitop3:0xe4
	v_bitop3_b32 v59, v59, s33, v238 bitop3:0xe4
	v_bitop3_b32 v44, v44, s33, v239 bitop3:0xe4
	v_bitop3_b32 v60, v60, s33, v240 bitop3:0xe4
	v_bitop3_b32 v45, v45, s33, v241 bitop3:0xe4
	v_bitop3_b32 v61, v61, s33, v242 bitop3:0xe4
	v_max3_f32 v243, v243, v42, v58
	v_max3_f32 v248, v248, v43, v59
	v_max3_f32 v243, v243, v44, v60
	s_waitcnt lgkmcnt(8)
	v_mfma_f32_32x32x16_bf16 v[0:15], v[178:181], v[94:97], v[0:15]
	ds_read_b128 v[142:145], v226 offset:24576
	v_max3_f32 v248, v248, v45, v61
	v_bfe_i32 v235, v249, 24, 1
	v_bfe_i32 v236, v250, 24, 1
	v_bfe_i32 v237, v249, 25, 1
	v_bfe_i32 v238, v250, 25, 1
	v_bfe_i32 v239, v249, 26, 1
	v_bfe_i32 v240, v250, 26, 1
	v_bfe_i32 v241, v249, 27, 1
	v_bfe_i32 v242, v250, 27, 1
	v_bitop3_b32 v46, v46, s33, v235 bitop3:0xe4
	v_bitop3_b32 v62, v62, s33, v236 bitop3:0xe4
	v_bitop3_b32 v47, v47, s33, v237 bitop3:0xe4
	s_waitcnt lgkmcnt(7)
	v_mfma_f32_32x32x16_bf16 v[16:31], v[182:185], v[94:97], v[16:31]
	ds_read_b128 v[146:149], v226 offset:28672
	v_bitop3_b32 v63, v63, s33, v238 bitop3:0xe4
	v_bitop3_b32 v48, v48, s33, v239 bitop3:0xe4
	v_bitop3_b32 v64, v64, s33, v240 bitop3:0xe4
	v_bitop3_b32 v49, v49, s33, v241 bitop3:0xe4
	v_bitop3_b32 v65, v65, s33, v242 bitop3:0xe4
	v_max3_f32 v243, v243, v46, v62
	v_max3_f32 v248, v248, v47, v63
	v_max3_f32 v243, v243, v48, v64
	v_max3_f32 v248, v248, v49, v65
	v_max_f32_e32 v243, v243, v248
	v_mov_b32_e32 v248, v243
	s_nop 1
	v_permlane32_swap_b32_e32 v243, v248
	v_max3_f32 v243, v230, v243, v248
	v_cmp_neq_f32_e32 vcc, s33, v243
	s_nop 1
	v_cndmask_b32_e32 v248, 0, v243, vcc
	v_sub_f32_e32 v33, v230, v248
	v_mul_f32_e32 v33, 0x3e38aa3b, v33
	v_exp_f32_e32 v232, v33
	v_mul_f32_e32 v234, 0xbe38aa3b, v248
	v_mov_b32_e32 v230, v243
	s_waitcnt vmcnt(2)
	s_barrier
	s_add_u32 s8, s8, 1
	s_cmp_lt_u32 s8, s9
	s_cbranch_scc1 .Lat_loop_2
	s_branch .Lat_epilogue

.Lat_nors_l1:
	v_fmamk_f32 v70, v70, 0x3e38aa3b, v234
	v_fmamk_f32 v71, v71, 0x3e38aa3b, v234
	v_fmamk_f32 v72, v72, 0x3e38aa3b, v234
	ds_read_b64_tr_b16 v[168:169], v228 offset:11264
	s_waitcnt lgkmcnt(14)
	v_fmamk_f32 v73, v73, 0x3e38aa3b, v234
	v_fmamk_f32 v74, v74, 0x3e38aa3b, v234
	v_fmamk_f32 v75, v75, 0x3e38aa3b, v234
	ds_read_b64_tr_b16 v[170:171], v227 offset:12288
	s_waitcnt lgkmcnt(14)
	v_fmamk_f32 v76, v76, 0x3e38aa3b, v234
	v_fmamk_f32 v77, v77, 0x3e38aa3b, v234
	v_exp_f32_e32 v70, v70
	ds_read_b64_tr_b16 v[172:173], v227 offset:13312
	s_waitcnt lgkmcnt(14)
	v_exp_f32_e32 v71, v71
	v_exp_f32_e32 v72, v72
	v_exp_f32_e32 v73, v73
	ds_read_b64_tr_b16 v[174:175], v228 offset:12288
	s_waitcnt lgkmcnt(14)
	v_exp_f32_e32 v74, v74
	v_exp_f32_e32 v75, v75
	v_exp_f32_e32 v76, v76
	ds_read_b64_tr_b16 v[176:177], v228 offset:13312
	s_waitcnt lgkmcnt(14)
	v_exp_f32_e32 v77, v77
	v_pk_add_f32 v[244:245], v[70:71], v[74:75]
	v_pk_add_f32 v[246:247], v[72:73], v[76:77]
	ds_read_b64_tr_b16 v[178:179], v227 offset:14336
	s_waitcnt lgkmcnt(14)
	v_cvt_pk_bf16_f32 v70, v70, v71
	v_cvt_pk_bf16_f32 v71, v72, v73
	v_cvt_pk_bf16_f32 v72, v74, v75
	ds_read_b64_tr_b16 v[180:181], v227 offset:15360
	s_waitcnt lgkmcnt(14)
	v_cvt_pk_bf16_f32 v73, v76, v77
	s_waitcnt lgkmcnt(12)
	v_mfma_f32_32x32x16_bf16 v[0:15], v[154:157], v[70:73], v[0:15]
	s_waitcnt lgkmcnt(10)
	v_mfma_f32_32x32x16_bf16 v[16:31], v[158:161], v[70:73], v[16:31]
	v_fmamk_f32 v78, v78, 0x3e38aa3b, v234
	v_fmamk_f32 v79, v79, 0x3e38aa3b, v234
	v_fmamk_f32 v80, v80, 0x3e38aa3b, v234
	ds_read_b64_tr_b16 v[182:183], v228 offset:14336
	v_fmamk_f32 v81, v81, 0x3e38aa3b, v234
	v_fmamk_f32 v82, v82, 0x3e38aa3b, v234
	v_fmamk_f32 v83, v83, 0x3e38aa3b, v234
	ds_read_b64_tr_b16 v[184:185], v228 offset:15360
	v_fmamk_f32 v84, v84, 0x3e38aa3b, v234
	v_fmamk_f32 v85, v85, 0x3e38aa3b, v234
	v_exp_f32_e32 v78, v78
	v_exp_f32_e32 v79, v79
	v_exp_f32_e32 v80, v80
	v_exp_f32_e32 v81, v81
	v_exp_f32_e32 v82, v82
	v_exp_f32_e32 v83, v83
	v_exp_f32_e32 v84, v84
	v_exp_f32_e32 v85, v85
	v_pk_add_f32 v[244:245], v[244:245], v[78:79]
	v_pk_add_f32 v[246:247], v[246:247], v[80:81]
	v_pk_add_f32 v[244:245], v[244:245], v[82:83]
	v_pk_add_f32 v[246:247], v[246:247], v[84:85]
	v_cvt_pk_bf16_f32 v78, v78, v79
	v_cvt_pk_bf16_f32 v79, v80, v81
	v_cvt_pk_bf16_f32 v80, v82, v83
	v_cvt_pk_bf16_f32 v81, v84, v85
	s_waitcnt lgkmcnt(10)
	v_mfma_f32_32x32x16_bf16 v[0:15], v[162:165], v[78:81], v[0:15]
	s_waitcnt lgkmcnt(8)
	v_mfma_f32_32x32x16_bf16 v[16:31], v[166:169], v[78:81], v[16:31]
	v_fmamk_f32 v86, v86, 0x3e38aa3b, v234
	v_fmamk_f32 v87, v87, 0x3e38aa3b, v234
	v_fmamk_f32 v88, v88, 0x3e38aa3b, v234
	v_fmamk_f32 v89, v89, 0x3e38aa3b, v234
	v_fmamk_f32 v90, v90, 0x3e38aa3b, v234
	v_fmamk_f32 v91, v91, 0x3e38aa3b, v234
	v_fmamk_f32 v92, v92, 0x3e38aa3b, v234
	v_fmamk_f32 v93, v93, 0x3e38aa3b, v234
	v_exp_f32_e32 v86, v86
	v_exp_f32_e32 v87, v87
	v_exp_f32_e32 v88, v88
	v_exp_f32_e32 v89, v89
	v_exp_f32_e32 v90, v90
	v_exp_f32_e32 v91, v91
	v_exp_f32_e32 v92, v92
	v_exp_f32_e32 v93, v93
	v_pk_add_f32 v[244:245], v[244:245], v[86:87]
	v_pk_add_f32 v[246:247], v[246:247], v[88:89]
	v_pk_add_f32 v[244:245], v[244:245], v[90:91]
	v_pk_add_f32 v[246:247], v[246:247], v[92:93]
	v_cvt_pk_bf16_f32 v86, v86, v87
	v_cvt_pk_bf16_f32 v87, v88, v89
	v_cvt_pk_bf16_f32 v88, v90, v91
	v_cvt_pk_bf16_f32 v89, v92, v93
	s_waitcnt lgkmcnt(6)
	v_mfma_f32_32x32x16_bf16 v[0:15], v[170:173], v[86:89], v[0:15]
	s_waitcnt lgkmcnt(4)
	v_mfma_f32_32x32x16_bf16 v[16:31], v[174:177], v[86:89], v[16:31]
	v_fmamk_f32 v94, v94, 0x3e38aa3b, v234
	v_fmamk_f32 v95, v95, 0x3e38aa3b, v234
	v_fmamk_f32 v96, v96, 0x3e38aa3b, v234
	v_fmamk_f32 v97, v97, 0x3e38aa3b, v234
	v_fmamk_f32 v98, v98, 0x3e38aa3b, v234
	v_fmamk_f32 v99, v99, 0x3e38aa3b, v234
	v_fmamk_f32 v100, v100, 0x3e38aa3b, v234
	v_fmamk_f32 v101, v101, 0x3e38aa3b, v234
	v_exp_f32_e32 v94, v94
	v_exp_f32_e32 v95, v95
	v_exp_f32_e32 v96, v96
	v_exp_f32_e32 v97, v97
	v_exp_f32_e32 v98, v98
	v_exp_f32_e32 v99, v99
	v_exp_f32_e32 v100, v100
	v_exp_f32_e32 v101, v101
	v_pk_add_f32 v[244:245], v[244:245], v[94:95]
	v_pk_add_f32 v[246:247], v[246:247], v[96:97]
	v_pk_add_f32 v[244:245], v[244:245], v[98:99]
	v_pk_add_f32 v[246:247], v[246:247], v[100:101]
	v_cvt_pk_bf16_f32 v94, v94, v95
	v_cvt_pk_bf16_f32 v95, v96, v97
	v_cvt_pk_bf16_f32 v96, v98, v99
	v_cvt_pk_bf16_f32 v97, v100, v101
	v_add_f32_e32 v244, v244, v245
	v_add_f32_e32 v246, v246, v247
	v_add_f32_e32 v244, v244, v246
	v_fma_f32 v231, v231, v232, v244
	s_waitcnt lgkmcnt(2)
	v_mfma_f32_32x32x16_bf16 v[0:15], v[178:181], v[94:97], v[0:15]
	s_waitcnt lgkmcnt(0)
	v_mfma_f32_32x32x16_bf16 v[16:31], v[182:185], v[94:97], v[16:31]
	s_waitcnt vmcnt(2)
	s_barrier
	s_add_u32 s8, s8, 1
	s_cmp_lt_u32 s8, s9
	s_cbranch_scc1 .Lat_loop_2
	s_branch .Lat_epilogue

.Lat_nors_f2:
	v_fmamk_f32 v34, v34, 0x3e38aa3b, v234
	v_fmamk_f32 v35, v35, 0x3e38aa3b, v234
	s_waitcnt lgkmcnt(7)
	v_mfma_f32_32x32x16_bf16 v[70:85], v[118:121], v[102:105], 0
	ds_read_b64_tr_b16 v[154:155], v227 offset:16384
	ds_read_b64_tr_b16 v[156:157], v227 offset:17408
	v_fmamk_f32 v36, v36, 0x3e38aa3b, v234
	v_fmamk_f32 v37, v37, 0x3e38aa3b, v234
	v_fmamk_f32 v38, v38, 0x3e38aa3b, v234
	v_fmamk_f32 v39, v39, 0x3e38aa3b, v234
	v_fmamk_f32 v40, v40, 0x3e38aa3b, v234
	v_fmamk_f32 v41, v41, 0x3e38aa3b, v234
	v_exp_f32_e32 v34, v34
	v_exp_f32_e32 v35, v35
	v_exp_f32_e32 v36, v36
	v_exp_f32_e32 v37, v37
	s_waitcnt lgkmcnt(8)
	v_mfma_f32_32x32x16_bf16 v[86:101], v[122:125], v[102:105], 0
	ds_read_b64_tr_b16 v[158:159], v228 offset:16384
	ds_read_b64_tr_b16 v[160:161], v228 offset:17408
	v_exp_f32_e32 v38, v38
	v_exp_f32_e32 v39, v39
	v_exp_f32_e32 v40, v40
	v_exp_f32_e32 v41, v41
	v_pk_add_f32 v[244:245], v[34:35], v[38:39]
	v_pk_add_f32 v[246:247], v[36:37], v[40:41]
	v_cvt_pk_bf16_f32 v34, v34, v35
	v_cvt_pk_bf16_f32 v35, v36, v37
	v_cvt_pk_bf16_f32 v36, v38, v39
	v_cvt_pk_bf16_f32 v37, v40, v41
	v_fmamk_f32 v42, v42, 0x3e38aa3b, v234
	s_waitcnt lgkmcnt(9)
	v_mfma_f32_32x32x16_bf16 v[70:85], v[126:129], v[106:109], v[70:85]
	ds_read_b64_tr_b16 v[162:163], v227 offset:18432
	ds_read_b64_tr_b16 v[164:165], v227 offset:19456
	v_fmamk_f32 v43, v43, 0x3e38aa3b, v234
	v_fmamk_f32 v44, v44, 0x3e38aa3b, v234
	v_fmamk_f32 v45, v45, 0x3e38aa3b, v234
	v_fmamk_f32 v46, v46, 0x3e38aa3b, v234
	v_fmamk_f32 v47, v47, 0x3e38aa3b, v234
	v_fmamk_f32 v48, v48, 0x3e38aa3b, v234
	v_fmamk_f32 v49, v49, 0x3e38aa3b, v234
	v_exp_f32_e32 v42, v42
	v_exp_f32_e32 v43, v43
	v_exp_f32_e32 v44, v44
	s_waitcnt lgkmcnt(10)
	v_mfma_f32_32x32x16_bf16 v[86:101], v[130:133], v[106:109], v[86:101]
	ds_read_b64_tr_b16 v[166:167], v228 offset:18432
	ds_read_b64_tr_b16 v[168:169], v228 offset:19456
	v_exp_f32_e32 v45, v45
	v_exp_f32_e32 v46, v46
	v_exp_f32_e32 v47, v47
	v_exp_f32_e32 v48, v48
	v_exp_f32_e32 v49, v49
	v_pk_add_f32 v[244:245], v[244:245], v[42:43]
	v_pk_add_f32 v[246:247], v[246:247], v[44:45]
	v_pk_add_f32 v[244:245], v[244:245], v[46:47]
	v_pk_add_f32 v[246:247], v[246:247], v[48:49]
	v_cvt_pk_bf16_f32 v42, v42, v43
	v_cvt_pk_bf16_f32 v43, v44, v45
	s_waitcnt lgkmcnt(11)
	v_mfma_f32_32x32x16_bf16 v[70:85], v[134:137], v[110:113], v[70:85]
	ds_read_b64_tr_b16 v[170:171], v227 offset:20480
	ds_read_b64_tr_b16 v[172:173], v227 offset:21504
	v_cvt_pk_bf16_f32 v44, v46, v47
	v_cvt_pk_bf16_f32 v45, v48, v49
	v_fmamk_f32 v50, v50, 0x3e38aa3b, v234
	v_fmamk_f32 v51, v51, 0x3e38aa3b, v234
	v_fmamk_f32 v52, v52, 0x3e38aa3b, v234
	v_fmamk_f32 v53, v53, 0x3e38aa3b, v234
	v_fmamk_f32 v54, v54, 0x3e38aa3b, v234
	v_fmamk_f32 v55, v55, 0x3e38aa3b, v234
	v_fmamk_f32 v56, v56, 0x3e38aa3b, v234
	v_fmamk_f32 v57, v57, 0x3e38aa3b, v234
	s_waitcnt lgkmcnt(12)
	v_mfma_f32_32x32x16_bf16 v[86:101], v[138:141], v[110:113], v[86:101]
	ds_read_b64_tr_b16 v[174:175], v228 offset:20480
	ds_read_b64_tr_b16 v[176:177], v228 offset:21504
	v_exp_f32_e32 v50, v50
	v_exp_f32_e32 v51, v51
	v_exp_f32_e32 v52, v52
	v_exp_f32_e32 v53, v53
	v_exp_f32_e32 v54, v54
	v_exp_f32_e32 v55, v55
	v_exp_f32_e32 v56, v56
	v_exp_f32_e32 v57, v57
	v_pk_add_f32 v[244:245], v[244:245], v[50:51]
	v_pk_add_f32 v[246:247], v[246:247], v[52:53]
	v_pk_add_f32 v[244:245], v[244:245], v[54:55]
	s_waitcnt lgkmcnt(13)
	v_mfma_f32_32x32x16_bf16 v[70:85], v[142:145], v[114:117], v[70:85]
	ds_read_b64_tr_b16 v[178:179], v227 offset:22528
	ds_read_b64_tr_b16 v[180:181], v227 offset:23552
	v_pk_add_f32 v[246:247], v[246:247], v[56:57]
	v_cvt_pk_bf16_f32 v50, v50, v51
	v_cvt_pk_bf16_f32 v51, v52, v53
	v_cvt_pk_bf16_f32 v52, v54, v55
	v_cvt_pk_bf16_f32 v53, v56, v57
	v_fmamk_f32 v58, v58, 0x3e38aa3b, v234
	v_fmamk_f32 v59, v59, 0x3e38aa3b, v234
	v_fmamk_f32 v60, v60, 0x3e38aa3b, v234
	v_fmamk_f32 v61, v61, 0x3e38aa3b, v234
	v_fmamk_f32 v62, v62, 0x3e38aa3b, v234
	s_waitcnt lgkmcnt(14)
	v_mfma_f32_32x32x16_bf16 v[86:101], v[146:149], v[114:117], v[86:101]
	ds_read_b64_tr_b16 v[182:183], v228 offset:22528
	ds_read_b64_tr_b16 v[184:185], v228 offset:23552
	s_waitcnt lgkmcnt(14)
	v_fmamk_f32 v63, v63, 0x3e38aa3b, v234
	v_fmamk_f32 v64, v64, 0x3e38aa3b, v234
	v_fmamk_f32 v65, v65, 0x3e38aa3b, v234
	v_exp_f32_e32 v58, v58
	v_exp_f32_e32 v59, v59
	v_exp_f32_e32 v60, v60
	v_exp_f32_e32 v61, v61
	v_exp_f32_e32 v62, v62
	v_exp_f32_e32 v63, v63
	v_exp_f32_e32 v64, v64
	v_exp_f32_e32 v65, v65
	v_pk_add_f32 v[244:245], v[244:245], v[58:59]
	v_pk_add_f32 v[246:247], v[246:247], v[60:61]
	s_waitcnt lgkmcnt(14)
	v_mfma_f32_32x32x16_bf16 v[0:15], v[154:157], v[34:37], v[0:15]
	ds_read_b128 v[118:121], v223 offset:0
	v_pk_add_f32 v[244:245], v[244:245], v[62:63]
	v_pk_add_f32 v[246:247], v[246:247], v[64:65]
	v_cvt_pk_bf16_f32 v58, v58, v59
	v_cvt_pk_bf16_f32 v59, v60, v61
	v_cvt_pk_bf16_f32 v60, v62, v63
	v_cvt_pk_bf16_f32 v61, v64, v65
	v_add_f32_e32 v244, v244, v245
	v_add_f32_e32 v246, v246, v247
	v_add_f32_e32 v244, v244, v246
	v_fma_f32 v231, v231, v232, v244
	v_lshrrev_b32_e32 v249, v229, v204
	s_waitcnt lgkmcnt(13)
	v_mfma_f32_32x32x16_bf16 v[16:31], v[158:161], v[34:37], v[16:31]
	ds_read_b128 v[122:125], v223 offset:4096
	v_lshrrev_b32_e32 v250, v229, v205
	v_bfe_i32 v235, v249, 0, 1
	v_bfe_i32 v236, v250, 0, 1
	v_bfe_i32 v237, v249, 1, 1
	v_bfe_i32 v238, v250, 1, 1
	v_bfe_i32 v239, v249, 2, 1
	v_bfe_i32 v240, v250, 2, 1
	v_bfe_i32 v241, v249, 3, 1
	v_bfe_i32 v242, v250, 3, 1
	v_bitop3_b32 v70, v70, s33, v235 bitop3:0xe4
	v_bitop3_b32 v86, v86, s33, v236 bitop3:0xe4
	v_bitop3_b32 v71, v71, s33, v237 bitop3:0xe4
	s_waitcnt lgkmcnt(12)
	v_mfma_f32_32x32x16_bf16 v[0:15], v[162:165], v[42:45], v[0:15]
	ds_read_b128 v[126:129], v224 offset:0
	v_bitop3_b32 v87, v87, s33, v238 bitop3:0xe4
	v_bitop3_b32 v72, v72, s33, v239 bitop3:0xe4
	v_bitop3_b32 v88, v88, s33, v240 bitop3:0xe4
	v_bitop3_b32 v73, v73, s33, v241 bitop3:0xe4
	v_bitop3_b32 v89, v89, s33, v242 bitop3:0xe4
	v_max3_f32 v243, v70, s33, v86
	v_max3_f32 v248, v71, s33, v87
	v_max3_f32 v243, v243, v72, v88
	v_max3_f32 v248, v248, v73, v89
	v_bfe_i32 v235, v249, 8, 1
	v_bfe_i32 v236, v250, 8, 1
	v_bfe_i32 v237, v249, 9, 1
	s_waitcnt lgkmcnt(11)
	v_mfma_f32_32x32x16_bf16 v[16:31], v[166:169], v[42:45], v[16:31]
	ds_read_b128 v[130:133], v224 offset:4096
	v_bfe_i32 v238, v250, 9, 1
	v_bfe_i32 v239, v249, 10, 1
	v_bfe_i32 v240, v250, 10, 1
	v_bfe_i32 v241, v249, 11, 1
	v_bfe_i32 v242, v250, 11, 1
	v_bitop3_b32 v74, v74, s33, v235 bitop3:0xe4
	v_bitop3_b32 v90, v90, s33, v236 bitop3:0xe4
	v_bitop3_b32 v75, v75, s33, v237 bitop3:0xe4
	v_bitop3_b32 v91, v91, s33, v238 bitop3:0xe4
	v_bitop3_b32 v76, v76, s33, v239 bitop3:0xe4
	v_bitop3_b32 v92, v92, s33, v240 bitop3:0xe4
	v_bitop3_b32 v77, v77, s33, v241 bitop3:0xe4
	s_waitcnt lgkmcnt(10)
	v_mfma_f32_32x32x16_bf16 v[0:15], v[170:173], v[50:53], v[0:15]
	ds_read_b128 v[134:137], v225 offset:0
	v_bitop3_b32 v93, v93, s33, v242 bitop3:0xe4
	v_max3_f32 v243, v243, v74, v90
	v_max3_f32 v248, v248, v75, v91
	v_max3_f32 v243, v243, v76, v92
	v_max3_f32 v248, v248, v77, v93
	v_bfe_i32 v235, v249, 16, 1
	v_bfe_i32 v236, v250, 16, 1
	v_bfe_i32 v237, v249, 17, 1
	v_bfe_i32 v238, v250, 17, 1
	v_bfe_i32 v239, v249, 18, 1
	v_bfe_i32 v240, v250, 18, 1
	v_bfe_i32 v241, v249, 19, 1
	s_waitcnt lgkmcnt(9)
	v_mfma_f32_32x32x16_bf16 v[16:31], v[174:177], v[50:53], v[16:31]
	ds_read_b128 v[138:141], v225 offset:4096
	v_bfe_i32 v242, v250, 19, 1
	v_bitop3_b32 v78, v78, s33, v235 bitop3:0xe4
	v_bitop3_b32 v94, v94, s33, v236 bitop3:0xe4
	v_bitop3_b32 v79, v79, s33, v237 bitop3:0xe4
	v_bitop3_b32 v95, v95, s33, v238 bitop3:0xe4
	v_bitop3_b32 v80, v80, s33, v239 bitop3:0xe4
	v_bitop3_b32 v96, v96, s33, v240 bitop3:0xe4
	v_bitop3_b32 v81, v81, s33, v241 bitop3:0xe4
	v_bitop3_b32 v97, v97, s33, v242 bitop3:0xe4
	v_max3_f32 v243, v243, v78, v94
	v_max3_f32 v248, v248, v79, v95
	v_max3_f32 v243, v243, v80, v96
	s_waitcnt lgkmcnt(8)
	v_mfma_f32_32x32x16_bf16 v[0:15], v[178:181], v[58:61], v[0:15]
	ds_read_b128 v[142:145], v226 offset:0
	v_max3_f32 v248, v248, v81, v97
	v_bfe_i32 v235, v249, 24, 1
	v_bfe_i32 v236, v250, 24, 1
	v_bfe_i32 v237, v249, 25, 1
	v_bfe_i32 v238, v250, 25, 1
	v_bfe_i32 v239, v249, 26, 1
	v_bfe_i32 v240, v250, 26, 1
	v_bfe_i32 v241, v249, 27, 1
	v_bfe_i32 v242, v250, 27, 1
	v_bitop3_b32 v82, v82, s33, v235 bitop3:0xe4
	v_bitop3_b32 v98, v98, s33, v236 bitop3:0xe4
	v_bitop3_b32 v83, v83, s33, v237 bitop3:0xe4
	s_waitcnt lgkmcnt(7)
	v_mfma_f32_32x32x16_bf16 v[16:31], v[182:185], v[58:61], v[16:31]
	ds_read_b128 v[146:149], v226 offset:4096
	v_bitop3_b32 v99, v99, s33, v238 bitop3:0xe4
	v_bitop3_b32 v84, v84, s33, v239 bitop3:0xe4
	v_bitop3_b32 v100, v100, s33, v240 bitop3:0xe4
	v_bitop3_b32 v85, v85, s33, v241 bitop3:0xe4
	v_bitop3_b32 v101, v101, s33, v242 bitop3:0xe4
	v_max3_f32 v243, v243, v82, v98
	v_max3_f32 v248, v248, v83, v99
	v_max3_f32 v243, v243, v84, v100
	v_max3_f32 v248, v248, v85, v101
	v_max_f32_e32 v243, v243, v248
	v_mov_b32_e32 v248, v243
	s_nop 1
	v_permlane32_swap_b32_e32 v243, v248
	v_max3_f32 v243, v230, v243, v248
	v_cmp_neq_f32_e32 vcc, s33, v243
	s_nop 1
	v_cndmask_b32_e32 v248, 0, v243, vcc
	v_sub_f32_e32 v33, v230, v248
	v_mul_f32_e32 v33, 0x3e38aa3b, v33
	v_exp_f32_e32 v232, v33
	v_mul_f32_e32 v234, 0xbe38aa3b, v248
	v_mov_b32_e32 v230, v243
	s_waitcnt vmcnt(3)
	s_barrier
	s_add_u32 s8, s8, 1
	s_cmp_lt_u32 s8, s9
	s_cbranch_scc1 .Lat_loop_3
	s_branch .Lat_epilogue

.Lat_nors_l2:
	v_fmamk_f32 v34, v34, 0x3e38aa3b, v234
	v_fmamk_f32 v35, v35, 0x3e38aa3b, v234
	v_fmamk_f32 v36, v36, 0x3e38aa3b, v234
	ds_read_b64_tr_b16 v[168:169], v228 offset:19456
	s_waitcnt lgkmcnt(14)
	v_fmamk_f32 v37, v37, 0x3e38aa3b, v234
	v_fmamk_f32 v38, v38, 0x3e38aa3b, v234
	v_fmamk_f32 v39, v39, 0x3e38aa3b, v234
	ds_read_b64_tr_b16 v[170:171], v227 offset:20480
	s_waitcnt lgkmcnt(14)
	v_fmamk_f32 v40, v40, 0x3e38aa3b, v234
	v_fmamk_f32 v41, v41, 0x3e38aa3b, v234
	v_exp_f32_e32 v34, v34
	ds_read_b64_tr_b16 v[172:173], v227 offset:21504
	s_waitcnt lgkmcnt(14)
	v_exp_f32_e32 v35, v35
	v_exp_f32_e32 v36, v36
	v_exp_f32_e32 v37, v37
	ds_read_b64_tr_b16 v[174:175], v228 offset:20480
	s_waitcnt lgkmcnt(14)
	v_exp_f32_e32 v38, v38
	v_exp_f32_e32 v39, v39
	v_exp_f32_e32 v40, v40
	ds_read_b64_tr_b16 v[176:177], v228 offset:21504
	s_waitcnt lgkmcnt(14)
	v_exp_f32_e32 v41, v41
	v_pk_add_f32 v[244:245], v[34:35], v[38:39]
	v_pk_add_f32 v[246:247], v[36:37], v[40:41]
	ds_read_b64_tr_b16 v[178:179], v227 offset:22528
	s_waitcnt lgkmcnt(14)
	v_cvt_pk_bf16_f32 v34, v34, v35
	v_cvt_pk_bf16_f32 v35, v36, v37
	v_cvt_pk_bf16_f32 v36, v38, v39
	ds_read_b64_tr_b16 v[180:181], v227 offset:23552
	s_waitcnt lgkmcnt(14)
	v_cvt_pk_bf16_f32 v37, v40, v41
	s_waitcnt lgkmcnt(12)
	v_mfma_f32_32x32x16_bf16 v[0:15], v[154:157], v[34:37], v[0:15]
	s_waitcnt lgkmcnt(10)
	v_mfma_f32_32x32x16_bf16 v[16:31], v[158:161], v[34:37], v[16:31]
	v_fmamk_f32 v42, v42, 0x3e38aa3b, v234
	v_fmamk_f32 v43, v43, 0x3e38aa3b, v234
	v_fmamk_f32 v44, v44, 0x3e38aa3b, v234
	ds_read_b64_tr_b16 v[182:183], v228 offset:22528
	v_fmamk_f32 v45, v45, 0x3e38aa3b, v234
	v_fmamk_f32 v46, v46, 0x3e38aa3b, v234
	v_fmamk_f32 v47, v47, 0x3e38aa3b, v234
	ds_read_b64_tr_b16 v[184:185], v228 offset:23552
	v_fmamk_f32 v48, v48, 0x3e38aa3b, v234
	v_fmamk_f32 v49, v49, 0x3e38aa3b, v234
	v_exp_f32_e32 v42, v42
	v_exp_f32_e32 v43, v43
	v_exp_f32_e32 v44, v44
	v_exp_f32_e32 v45, v45
	v_exp_f32_e32 v46, v46
	v_exp_f32_e32 v47, v47
	v_exp_f32_e32 v48, v48
	v_exp_f32_e32 v49, v49
	v_pk_add_f32 v[244:245], v[244:245], v[42:43]
	v_pk_add_f32 v[246:247], v[246:247], v[44:45]
	v_pk_add_f32 v[244:245], v[244:245], v[46:47]
	v_pk_add_f32 v[246:247], v[246:247], v[48:49]
	v_cvt_pk_bf16_f32 v42, v42, v43
	v_cvt_pk_bf16_f32 v43, v44, v45
	v_cvt_pk_bf16_f32 v44, v46, v47
	v_cvt_pk_bf16_f32 v45, v48, v49
	s_waitcnt lgkmcnt(10)
	v_mfma_f32_32x32x16_bf16 v[0:15], v[162:165], v[42:45], v[0:15]
	s_waitcnt lgkmcnt(8)
	v_mfma_f32_32x32x16_bf16 v[16:31], v[166:169], v[42:45], v[16:31]
	v_fmamk_f32 v50, v50, 0x3e38aa3b, v234
	v_fmamk_f32 v51, v51, 0x3e38aa3b, v234
	v_fmamk_f32 v52, v52, 0x3e38aa3b, v234
	v_fmamk_f32 v53, v53, 0x3e38aa3b, v234
	v_fmamk_f32 v54, v54, 0x3e38aa3b, v234
	v_fmamk_f32 v55, v55, 0x3e38aa3b, v234
	v_fmamk_f32 v56, v56, 0x3e38aa3b, v234
	v_fmamk_f32 v57, v57, 0x3e38aa3b, v234
	v_exp_f32_e32 v50, v50
	v_exp_f32_e32 v51, v51
	v_exp_f32_e32 v52, v52
	v_exp_f32_e32 v53, v53
	v_exp_f32_e32 v54, v54
	v_exp_f32_e32 v55, v55
	v_exp_f32_e32 v56, v56
	v_exp_f32_e32 v57, v57
	v_pk_add_f32 v[244:245], v[244:245], v[50:51]
	v_pk_add_f32 v[246:247], v[246:247], v[52:53]
	v_pk_add_f32 v[244:245], v[244:245], v[54:55]
	v_pk_add_f32 v[246:247], v[246:247], v[56:57]
	v_cvt_pk_bf16_f32 v50, v50, v51
	v_cvt_pk_bf16_f32 v51, v52, v53
	v_cvt_pk_bf16_f32 v52, v54, v55
	v_cvt_pk_bf16_f32 v53, v56, v57
	s_waitcnt lgkmcnt(6)
	v_mfma_f32_32x32x16_bf16 v[0:15], v[170:173], v[50:53], v[0:15]
	s_waitcnt lgkmcnt(4)
	v_mfma_f32_32x32x16_bf16 v[16:31], v[174:177], v[50:53], v[16:31]
	v_fmamk_f32 v58, v58, 0x3e38aa3b, v234
	v_fmamk_f32 v59, v59, 0x3e38aa3b, v234
	v_fmamk_f32 v60, v60, 0x3e38aa3b, v234
	v_fmamk_f32 v61, v61, 0x3e38aa3b, v234
	v_fmamk_f32 v62, v62, 0x3e38aa3b, v234
	v_fmamk_f32 v63, v63, 0x3e38aa3b, v234
	v_fmamk_f32 v64, v64, 0x3e38aa3b, v234
	v_fmamk_f32 v65, v65, 0x3e38aa3b, v234
	v_exp_f32_e32 v58, v58
	v_exp_f32_e32 v59, v59
	v_exp_f32_e32 v60, v60
	v_exp_f32_e32 v61, v61
	v_exp_f32_e32 v62, v62
	v_exp_f32_e32 v63, v63
	v_exp_f32_e32 v64, v64
	v_exp_f32_e32 v65, v65
	v_pk_add_f32 v[244:245], v[244:245], v[58:59]
	v_pk_add_f32 v[246:247], v[246:247], v[60:61]
	v_pk_add_f32 v[244:245], v[244:245], v[62:63]
	v_pk_add_f32 v[246:247], v[246:247], v[64:65]
	v_cvt_pk_bf16_f32 v58, v58, v59
	v_cvt_pk_bf16_f32 v59, v60, v61
	v_cvt_pk_bf16_f32 v60, v62, v63
	v_cvt_pk_bf16_f32 v61, v64, v65
	v_add_f32_e32 v244, v244, v245
	v_add_f32_e32 v246, v246, v247
	v_add_f32_e32 v244, v244, v246
	v_fma_f32 v231, v231, v232, v244
	s_waitcnt lgkmcnt(2)
	v_mfma_f32_32x32x16_bf16 v[0:15], v[178:181], v[58:61], v[0:15]
	s_waitcnt lgkmcnt(0)
	v_mfma_f32_32x32x16_bf16 v[16:31], v[182:185], v[58:61], v[16:31]
	s_waitcnt vmcnt(3)
	s_barrier
	s_add_u32 s8, s8, 1
	s_cmp_lt_u32 s8, s9
	s_cbranch_scc1 .Lat_loop_3
	s_branch .Lat_epilogue

.Lat_nors_f3:
	v_fmamk_f32 v70, v70, 0x3e38aa3b, v234
	v_fmamk_f32 v71, v71, 0x3e38aa3b, v234
	s_waitcnt lgkmcnt(7)
	v_mfma_f32_32x32x16_bf16 v[34:49], v[118:121], v[102:105], 0
	ds_read_b64_tr_b16 v[154:155], v227 offset:24576
	ds_read_b64_tr_b16 v[156:157], v227 offset:25600
	v_fmamk_f32 v72, v72, 0x3e38aa3b, v234
	v_fmamk_f32 v73, v73, 0x3e38aa3b, v234
	v_fmamk_f32 v74, v74, 0x3e38aa3b, v234
	v_fmamk_f32 v75, v75, 0x3e38aa3b, v234
	v_fmamk_f32 v76, v76, 0x3e38aa3b, v234
	v_fmamk_f32 v77, v77, 0x3e38aa3b, v234
	v_exp_f32_e32 v70, v70
	v_exp_f32_e32 v71, v71
	v_exp_f32_e32 v72, v72
	v_exp_f32_e32 v73, v73
	s_waitcnt lgkmcnt(8)
	v_mfma_f32_32x32x16_bf16 v[50:65], v[122:125], v[102:105], 0
	ds_read_b64_tr_b16 v[158:159], v228 offset:24576
	ds_read_b64_tr_b16 v[160:161], v228 offset:25600
	v_exp_f32_e32 v74, v74
	v_exp_f32_e32 v75, v75
	v_exp_f32_e32 v76, v76
	v_exp_f32_e32 v77, v77
	v_pk_add_f32 v[244:245], v[70:71], v[74:75]
	v_pk_add_f32 v[246:247], v[72:73], v[76:77]
	v_cvt_pk_bf16_f32 v70, v70, v71
	v_cvt_pk_bf16_f32 v71, v72, v73
	v_cvt_pk_bf16_f32 v72, v74, v75
	v_cvt_pk_bf16_f32 v73, v76, v77
	v_fmamk_f32 v78, v78, 0x3e38aa3b, v234
	s_waitcnt lgkmcnt(9)
	v_mfma_f32_32x32x16_bf16 v[34:49], v[126:129], v[106:109], v[34:49]
	ds_read_b64_tr_b16 v[162:163], v227 offset:26624
	ds_read_b64_tr_b16 v[164:165], v227 offset:27648
	v_fmamk_f32 v79, v79, 0x3e38aa3b, v234
	v_fmamk_f32 v80, v80, 0x3e38aa3b, v234
	v_fmamk_f32 v81, v81, 0x3e38aa3b, v234
	v_fmamk_f32 v82, v82, 0x3e38aa3b, v234
	v_fmamk_f32 v83, v83, 0x3e38aa3b, v234
	v_fmamk_f32 v84, v84, 0x3e38aa3b, v234
	v_fmamk_f32 v85, v85, 0x3e38aa3b, v234
	v_exp_f32_e32 v78, v78
	v_exp_f32_e32 v79, v79
	v_exp_f32_e32 v80, v80
	s_waitcnt lgkmcnt(10)
	v_mfma_f32_32x32x16_bf16 v[50:65], v[130:133], v[106:109], v[50:65]
	ds_read_b64_tr_b16 v[166:167], v228 offset:26624
	ds_read_b64_tr_b16 v[168:169], v228 offset:27648
	v_exp_f32_e32 v81, v81
	v_exp_f32_e32 v82, v82
	v_exp_f32_e32 v83, v83
	v_exp_f32_e32 v84, v84
	v_exp_f32_e32 v85, v85
	v_pk_add_f32 v[244:245], v[244:245], v[78:79]
	v_pk_add_f32 v[246:247], v[246:247], v[80:81]
	v_pk_add_f32 v[244:245], v[244:245], v[82:83]
	v_pk_add_f32 v[246:247], v[246:247], v[84:85]
	v_cvt_pk_bf16_f32 v78, v78, v79
	v_cvt_pk_bf16_f32 v79, v80, v81
	s_waitcnt lgkmcnt(11)
	v_mfma_f32_32x32x16_bf16 v[34:49], v[134:137], v[110:113], v[34:49]
	ds_read_b64_tr_b16 v[170:171], v227 offset:28672
	ds_read_b64_tr_b16 v[172:173], v227 offset:29696
	v_cvt_pk_bf16_f32 v80, v82, v83
	v_cvt_pk_bf16_f32 v81, v84, v85
	v_fmamk_f32 v86, v86, 0x3e38aa3b, v234
	v_fmamk_f32 v87, v87, 0x3e38aa3b, v234
	v_fmamk_f32 v88, v88, 0x3e38aa3b, v234
	v_fmamk_f32 v89, v89, 0x3e38aa3b, v234
	v_fmamk_f32 v90, v90, 0x3e38aa3b, v234
	v_fmamk_f32 v91, v91, 0x3e38aa3b, v234
	v_fmamk_f32 v92, v92, 0x3e38aa3b, v234
	v_fmamk_f32 v93, v93, 0x3e38aa3b, v234
	s_waitcnt lgkmcnt(12)
	v_mfma_f32_32x32x16_bf16 v[50:65], v[138:141], v[110:113], v[50:65]
	ds_read_b64_tr_b16 v[174:175], v228 offset:28672
	ds_read_b64_tr_b16 v[176:177], v228 offset:29696
	v_exp_f32_e32 v86, v86
	v_exp_f32_e32 v87, v87
	v_exp_f32_e32 v88, v88
	v_exp_f32_e32 v89, v89
	v_exp_f32_e32 v90, v90
	v_exp_f32_e32 v91, v91
	v_exp_f32_e32 v92, v92
	v_exp_f32_e32 v93, v93
	v_pk_add_f32 v[244:245], v[244:245], v[86:87]
	v_pk_add_f32 v[246:247], v[246:247], v[88:89]
	v_pk_add_f32 v[244:245], v[244:245], v[90:91]
	s_waitcnt lgkmcnt(13)
	v_mfma_f32_32x32x16_bf16 v[34:49], v[142:145], v[114:117], v[34:49]
	ds_read_b64_tr_b16 v[178:179], v227 offset:30720
	ds_read_b64_tr_b16 v[180:181], v227 offset:31744
	v_pk_add_f32 v[246:247], v[246:247], v[92:93]
	v_cvt_pk_bf16_f32 v86, v86, v87
	v_cvt_pk_bf16_f32 v87, v88, v89
	v_cvt_pk_bf16_f32 v88, v90, v91
	v_cvt_pk_bf16_f32 v89, v92, v93
	v_fmamk_f32 v94, v94, 0x3e38aa3b, v234
	v_fmamk_f32 v95, v95, 0x3e38aa3b, v234
	v_fmamk_f32 v96, v96, 0x3e38aa3b, v234
	v_fmamk_f32 v97, v97, 0x3e38aa3b, v234
	v_fmamk_f32 v98, v98, 0x3e38aa3b, v234
	s_waitcnt lgkmcnt(14)
	v_mfma_f32_32x32x16_bf16 v[50:65], v[146:149], v[114:117], v[50:65]
	ds_read_b64_tr_b16 v[182:183], v228 offset:30720
	ds_read_b64_tr_b16 v[184:185], v228 offset:31744
	s_waitcnt lgkmcnt(14)
	v_fmamk_f32 v99, v99, 0x3e38aa3b, v234
	v_fmamk_f32 v100, v100, 0x3e38aa3b, v234
	v_fmamk_f32 v101, v101, 0x3e38aa3b, v234
	v_exp_f32_e32 v94, v94
	v_exp_f32_e32 v95, v95
	v_exp_f32_e32 v96, v96
	v_exp_f32_e32 v97, v97
	v_exp_f32_e32 v98, v98
	v_exp_f32_e32 v99, v99
	v_exp_f32_e32 v100, v100
	v_exp_f32_e32 v101, v101
	v_pk_add_f32 v[244:245], v[244:245], v[94:95]
	v_pk_add_f32 v[246:247], v[246:247], v[96:97]
	s_waitcnt lgkmcnt(14)
	v_mfma_f32_32x32x16_bf16 v[0:15], v[154:157], v[70:73], v[0:15]
	ds_read_b128 v[118:121], v223 offset:8192
	v_pk_add_f32 v[244:245], v[244:245], v[98:99]
	v_pk_add_f32 v[246:247], v[246:247], v[100:101]
	v_cvt_pk_bf16_f32 v94, v94, v95
	v_cvt_pk_bf16_f32 v95, v96, v97
	v_cvt_pk_bf16_f32 v96, v98, v99
	v_cvt_pk_bf16_f32 v97, v100, v101
	v_add_f32_e32 v244, v244, v245
	v_add_f32_e32 v246, v246, v247
	v_add_f32_e32 v244, v244, v246
	v_fma_f32 v231, v231, v232, v244
	s_waitcnt vmcnt(4)
	v_lshrrev_b32_e32 v249, v229, v198
	s_waitcnt lgkmcnt(13)
	v_mfma_f32_32x32x16_bf16 v[16:31], v[158:161], v[70:73], v[16:31]
	ds_read_b128 v[122:125], v223 offset:12288
	v_lshrrev_b32_e32 v250, v229, v199
	v_bfe_i32 v235, v249, 0, 1
	v_bfe_i32 v236, v250, 0, 1
	v_bfe_i32 v237, v249, 1, 1
	v_bfe_i32 v238, v250, 1, 1
	v_bfe_i32 v239, v249, 2, 1
	v_bfe_i32 v240, v250, 2, 1
	v_bfe_i32 v241, v249, 3, 1
	v_bfe_i32 v242, v250, 3, 1
	v_bitop3_b32 v34, v34, s33, v235 bitop3:0xe4
	v_bitop3_b32 v50, v50, s33, v236 bitop3:0xe4
	v_bitop3_b32 v35, v35, s33, v237 bitop3:0xe4
	s_waitcnt lgkmcnt(12)
	v_mfma_f32_32x32x16_bf16 v[0:15], v[162:165], v[78:81], v[0:15]
	ds_read_b128 v[126:129], v224 offset:8192
	v_bitop3_b32 v51, v51, s33, v238 bitop3:0xe4
	v_bitop3_b32 v36, v36, s33, v239 bitop3:0xe4
	v_bitop3_b32 v52, v52, s33, v240 bitop3:0xe4
	v_bitop3_b32 v37, v37, s33, v241 bitop3:0xe4
	v_bitop3_b32 v53, v53, s33, v242 bitop3:0xe4
	v_max3_f32 v243, v34, s33, v50
	v_max3_f32 v248, v35, s33, v51
	v_max3_f32 v243, v243, v36, v52
	v_max3_f32 v248, v248, v37, v53
	v_bfe_i32 v235, v249, 8, 1
	v_bfe_i32 v236, v250, 8, 1
	v_bfe_i32 v237, v249, 9, 1
	s_waitcnt lgkmcnt(11)
	v_mfma_f32_32x32x16_bf16 v[16:31], v[166:169], v[78:81], v[16:31]
	ds_read_b128 v[130:133], v224 offset:12288
	v_bfe_i32 v238, v250, 9, 1
	v_bfe_i32 v239, v249, 10, 1
	v_bfe_i32 v240, v250, 10, 1
	v_bfe_i32 v241, v249, 11, 1
	v_bfe_i32 v242, v250, 11, 1
	v_bitop3_b32 v38, v38, s33, v235 bitop3:0xe4
	v_bitop3_b32 v54, v54, s33, v236 bitop3:0xe4
	v_bitop3_b32 v39, v39, s33, v237 bitop3:0xe4
	v_bitop3_b32 v55, v55, s33, v238 bitop3:0xe4
	v_bitop3_b32 v40, v40, s33, v239 bitop3:0xe4
	v_bitop3_b32 v56, v56, s33, v240 bitop3:0xe4
	v_bitop3_b32 v41, v41, s33, v241 bitop3:0xe4
	s_waitcnt lgkmcnt(10)
	v_mfma_f32_32x32x16_bf16 v[0:15], v[170:173], v[86:89], v[0:15]
	ds_read_b128 v[134:137], v225 offset:8192
	v_bitop3_b32 v57, v57, s33, v242 bitop3:0xe4
	v_max3_f32 v243, v243, v38, v54
	v_max3_f32 v248, v248, v39, v55
	v_max3_f32 v243, v243, v40, v56
	v_max3_f32 v248, v248, v41, v57
	v_bfe_i32 v235, v249, 16, 1
	v_bfe_i32 v236, v250, 16, 1
	v_bfe_i32 v237, v249, 17, 1
	v_bfe_i32 v238, v250, 17, 1
	v_bfe_i32 v239, v249, 18, 1
	v_bfe_i32 v240, v250, 18, 1
	v_bfe_i32 v241, v249, 19, 1
	s_waitcnt lgkmcnt(9)
	v_mfma_f32_32x32x16_bf16 v[16:31], v[174:177], v[86:89], v[16:31]
	ds_read_b128 v[138:141], v225 offset:12288
	v_bfe_i32 v242, v250, 19, 1
	v_bitop3_b32 v42, v42, s33, v235 bitop3:0xe4
	v_bitop3_b32 v58, v58, s33, v236 bitop3:0xe4
	v_bitop3_b32 v43, v43, s33, v237 bitop3:0xe4
	v_bitop3_b32 v59, v59, s33, v238 bitop3:0xe4
	v_bitop3_b32 v44, v44, s33, v239 bitop3:0xe4
	v_bitop3_b32 v60, v60, s33, v240 bitop3:0xe4
	v_bitop3_b32 v45, v45, s33, v241 bitop3:0xe4
	v_bitop3_b32 v61, v61, s33, v242 bitop3:0xe4
	v_max3_f32 v243, v243, v42, v58
	v_max3_f32 v248, v248, v43, v59
	v_max3_f32 v243, v243, v44, v60
	s_waitcnt lgkmcnt(8)
	v_mfma_f32_32x32x16_bf16 v[0:15], v[178:181], v[94:97], v[0:15]
	ds_read_b128 v[142:145], v226 offset:8192
	v_max3_f32 v248, v248, v45, v61
	v_bfe_i32 v235, v249, 24, 1
	v_bfe_i32 v236, v250, 24, 1
	v_bfe_i32 v237, v249, 25, 1
	v_bfe_i32 v238, v250, 25, 1
	v_bfe_i32 v239, v249, 26, 1
	v_bfe_i32 v240, v250, 26, 1
	v_bfe_i32 v241, v249, 27, 1
	v_bfe_i32 v242, v250, 27, 1
	v_bitop3_b32 v46, v46, s33, v235 bitop3:0xe4
	v_bitop3_b32 v62, v62, s33, v236 bitop3:0xe4
	v_bitop3_b32 v47, v47, s33, v237 bitop3:0xe4
	s_waitcnt lgkmcnt(7)
	v_mfma_f32_32x32x16_bf16 v[16:31], v[182:185], v[94:97], v[16:31]
	ds_read_b128 v[146:149], v226 offset:12288
	v_bitop3_b32 v63, v63, s33, v238 bitop3:0xe4
	v_bitop3_b32 v48, v48, s33, v239 bitop3:0xe4
	v_bitop3_b32 v64, v64, s33, v240 bitop3:0xe4
	v_bitop3_b32 v49, v49, s33, v241 bitop3:0xe4
	v_bitop3_b32 v65, v65, s33, v242 bitop3:0xe4
	v_max3_f32 v243, v243, v46, v62
	v_max3_f32 v248, v248, v47, v63
	v_max3_f32 v243, v243, v48, v64
	v_max3_f32 v248, v248, v49, v65
	v_max_f32_e32 v243, v243, v248
	v_mov_b32_e32 v248, v243
	s_nop 1
	v_permlane32_swap_b32_e32 v243, v248
	v_max3_f32 v243, v230, v243, v248
	v_cmp_neq_f32_e32 vcc, s33, v243
	s_nop 1
	v_cndmask_b32_e32 v248, 0, v243, vcc
	v_sub_f32_e32 v33, v230, v248
	v_mul_f32_e32 v33, 0x3e38aa3b, v33
	v_exp_f32_e32 v232, v33
	v_mul_f32_e32 v234, 0xbe38aa3b, v248
	v_mov_b32_e32 v230, v243
	s_waitcnt vmcnt(2)
	s_barrier
	s_add_u32 s8, s8, 1
	s_cmp_lt_u32 s8, s9
	s_cbranch_scc1 .Lat_loop_0
	s_branch .Lat_epilogue

.Lat_nors_l3:
	v_fmamk_f32 v70, v70, 0x3e38aa3b, v234
	v_fmamk_f32 v71, v71, 0x3e38aa3b, v234
	v_fmamk_f32 v72, v72, 0x3e38aa3b, v234
	ds_read_b64_tr_b16 v[168:169], v228 offset:27648
	s_waitcnt lgkmcnt(14)
	v_fmamk_f32 v73, v73, 0x3e38aa3b, v234
	v_fmamk_f32 v74, v74, 0x3e38aa3b, v234
	v_fmamk_f32 v75, v75, 0x3e38aa3b, v234
	ds_read_b64_tr_b16 v[170:171], v227 offset:28672
	s_waitcnt lgkmcnt(14)
	v_fmamk_f32 v76, v76, 0x3e38aa3b, v234
	v_fmamk_f32 v77, v77, 0x3e38aa3b, v234
	v_exp_f32_e32 v70, v70
	ds_read_b64_tr_b16 v[172:173], v227 offset:29696
	s_waitcnt lgkmcnt(14)
	v_exp_f32_e32 v71, v71
	v_exp_f32_e32 v72, v72
	v_exp_f32_e32 v73, v73
	ds_read_b64_tr_b16 v[174:175], v228 offset:28672
	s_waitcnt lgkmcnt(14)
	v_exp_f32_e32 v74, v74
	v_exp_f32_e32 v75, v75
	v_exp_f32_e32 v76, v76
	ds_read_b64_tr_b16 v[176:177], v228 offset:29696
	s_waitcnt lgkmcnt(14)
	v_exp_f32_e32 v77, v77
	v_pk_add_f32 v[244:245], v[70:71], v[74:75]
	v_pk_add_f32 v[246:247], v[72:73], v[76:77]
	ds_read_b64_tr_b16 v[178:179], v227 offset:30720
	s_waitcnt lgkmcnt(14)
	v_cvt_pk_bf16_f32 v70, v70, v71
	v_cvt_pk_bf16_f32 v71, v72, v73
	v_cvt_pk_bf16_f32 v72, v74, v75
	ds_read_b64_tr_b16 v[180:181], v227 offset:31744
	s_waitcnt lgkmcnt(14)
	v_cvt_pk_bf16_f32 v73, v76, v77
	s_waitcnt lgkmcnt(12)
	v_mfma_f32_32x32x16_bf16 v[0:15], v[154:157], v[70:73], v[0:15]
	s_waitcnt lgkmcnt(10)
	v_mfma_f32_32x32x16_bf16 v[16:31], v[158:161], v[70:73], v[16:31]
	v_fmamk_f32 v78, v78, 0x3e38aa3b, v234
	v_fmamk_f32 v79, v79, 0x3e38aa3b, v234
	v_fmamk_f32 v80, v80, 0x3e38aa3b, v234
	ds_read_b64_tr_b16 v[182:183], v228 offset:30720
	v_fmamk_f32 v81, v81, 0x3e38aa3b, v234
	v_fmamk_f32 v82, v82, 0x3e38aa3b, v234
	v_fmamk_f32 v83, v83, 0x3e38aa3b, v234
	ds_read_b64_tr_b16 v[184:185], v228 offset:31744
	v_fmamk_f32 v84, v84, 0x3e38aa3b, v234
	v_fmamk_f32 v85, v85, 0x3e38aa3b, v234
	v_exp_f32_e32 v78, v78
	v_exp_f32_e32 v79, v79
	v_exp_f32_e32 v80, v80
	v_exp_f32_e32 v81, v81
	v_exp_f32_e32 v82, v82
	v_exp_f32_e32 v83, v83
	v_exp_f32_e32 v84, v84
	v_exp_f32_e32 v85, v85
	v_pk_add_f32 v[244:245], v[244:245], v[78:79]
	v_pk_add_f32 v[246:247], v[246:247], v[80:81]
	v_pk_add_f32 v[244:245], v[244:245], v[82:83]
	v_pk_add_f32 v[246:247], v[246:247], v[84:85]
	v_cvt_pk_bf16_f32 v78, v78, v79
	v_cvt_pk_bf16_f32 v79, v80, v81
	v_cvt_pk_bf16_f32 v80, v82, v83
	v_cvt_pk_bf16_f32 v81, v84, v85
	s_waitcnt lgkmcnt(10)
	v_mfma_f32_32x32x16_bf16 v[0:15], v[162:165], v[78:81], v[0:15]
	s_waitcnt lgkmcnt(8)
	v_mfma_f32_32x32x16_bf16 v[16:31], v[166:169], v[78:81], v[16:31]
	v_fmamk_f32 v86, v86, 0x3e38aa3b, v234
	v_fmamk_f32 v87, v87, 0x3e38aa3b, v234
	v_fmamk_f32 v88, v88, 0x3e38aa3b, v234
	v_fmamk_f32 v89, v89, 0x3e38aa3b, v234
	v_fmamk_f32 v90, v90, 0x3e38aa3b, v234
	v_fmamk_f32 v91, v91, 0x3e38aa3b, v234
	v_fmamk_f32 v92, v92, 0x3e38aa3b, v234
	v_fmamk_f32 v93, v93, 0x3e38aa3b, v234
	v_exp_f32_e32 v86, v86
	v_exp_f32_e32 v87, v87
	v_exp_f32_e32 v88, v88
	v_exp_f32_e32 v89, v89
	v_exp_f32_e32 v90, v90
	v_exp_f32_e32 v91, v91
	v_exp_f32_e32 v92, v92
	v_exp_f32_e32 v93, v93
	v_pk_add_f32 v[244:245], v[244:245], v[86:87]
	v_pk_add_f32 v[246:247], v[246:247], v[88:89]
	v_pk_add_f32 v[244:245], v[244:245], v[90:91]
	v_pk_add_f32 v[246:247], v[246:247], v[92:93]
	v_cvt_pk_bf16_f32 v86, v86, v87
	v_cvt_pk_bf16_f32 v87, v88, v89
	v_cvt_pk_bf16_f32 v88, v90, v91
	v_cvt_pk_bf16_f32 v89, v92, v93
	s_waitcnt lgkmcnt(6)
	v_mfma_f32_32x32x16_bf16 v[0:15], v[170:173], v[86:89], v[0:15]
	s_waitcnt lgkmcnt(4)
	v_mfma_f32_32x32x16_bf16 v[16:31], v[174:177], v[86:89], v[16:31]
	v_fmamk_f32 v94, v94, 0x3e38aa3b, v234
	v_fmamk_f32 v95, v95, 0x3e38aa3b, v234
	v_fmamk_f32 v96, v96, 0x3e38aa3b, v234
	v_fmamk_f32 v97, v97, 0x3e38aa3b, v234
	v_fmamk_f32 v98, v98, 0x3e38aa3b, v234
	v_fmamk_f32 v99, v99, 0x3e38aa3b, v234
	v_fmamk_f32 v100, v100, 0x3e38aa3b, v234
	v_fmamk_f32 v101, v101, 0x3e38aa3b, v234
	v_exp_f32_e32 v94, v94
	v_exp_f32_e32 v95, v95
	v_exp_f32_e32 v96, v96
	v_exp_f32_e32 v97, v97
	v_exp_f32_e32 v98, v98
	v_exp_f32_e32 v99, v99
	v_exp_f32_e32 v100, v100
	v_exp_f32_e32 v101, v101
	v_pk_add_f32 v[244:245], v[244:245], v[94:95]
	v_pk_add_f32 v[246:247], v[246:247], v[96:97]
	v_pk_add_f32 v[244:245], v[244:245], v[98:99]
	v_pk_add_f32 v[246:247], v[246:247], v[100:101]
	v_cvt_pk_bf16_f32 v94, v94, v95
	v_cvt_pk_bf16_f32 v95, v96, v97
	v_cvt_pk_bf16_f32 v96, v98, v99
	v_cvt_pk_bf16_f32 v97, v100, v101
	v_add_f32_e32 v244, v244, v245
	v_add_f32_e32 v246, v246, v247
	v_add_f32_e32 v244, v244, v246
	v_fma_f32 v231, v231, v232, v244
	s_waitcnt lgkmcnt(2)
	v_mfma_f32_32x32x16_bf16 v[0:15], v[178:181], v[94:97], v[0:15]
	s_waitcnt lgkmcnt(0)
	v_mfma_f32_32x32x16_bf16 v[16:31], v[182:185], v[94:97], v[16:31]
	s_waitcnt vmcnt(2)
	s_barrier
	s_add_u32 s8, s8, 1
	s_cmp_lt_u32 s8, s9
	s_cbranch_scc1 .Lat_loop_0
	s_branch .Lat_epilogue
.Lat_epilogue:
	v_mov_b32_e32 v248, v231
	v_mov_b32_e32 v243, v231
	s_nop 1
	v_permlane32_swap_b32_e32 v243, v248
	v_add_f32_e32 v243, v243, v248
	v_div_scale_f32 v235, s[18:19], v243, v243, 1.0
	v_rcp_f32_e32 v236, v235
	v_div_scale_f32 v237, vcc, 1.0, v243, 1.0
	v_fma_f32 v238, -v235, v236, 1.0
	v_fmac_f32_e32 v236, v238, v236
	v_mul_f32_e32 v238, v237, v236
	v_fma_f32 v239, -v235, v238, v237
	v_fmac_f32_e32 v238, v239, v236
	v_fma_f32 v235, -v235, v238, v237
	v_div_fmas_f32 v235, v235, v236, v238
	v_div_fixup_f32 v33, v235, v243, 1.0
	v_mul_f32_e32 v235, v0, v33
	v_mul_f32_e32 v236, v1, v33
	v_mul_f32_e32 v237, v2, v33
	v_mul_f32_e32 v238, v3, v33
	v_cvt_pk_bf16_f32 v240, v235, v236
	v_cvt_pk_bf16_f32 v241, v237, v238
	global_store_dwordx2 v197, v[240:241], s[4:5] offset:0
	s_nop 0
	v_mul_f32_e32 v235, v4, v33
	v_mul_f32_e32 v236, v5, v33
	v_mul_f32_e32 v237, v6, v33
	v_mul_f32_e32 v238, v7, v33
	v_cvt_pk_bf16_f32 v240, v235, v236
	v_cvt_pk_bf16_f32 v241, v237, v238
	global_store_dwordx2 v197, v[240:241], s[4:5] offset:16
	s_nop 0
	v_mul_f32_e32 v235, v8, v33
	v_mul_f32_e32 v236, v9, v33
	v_mul_f32_e32 v237, v10, v33
	v_mul_f32_e32 v238, v11, v33
	v_cvt_pk_bf16_f32 v240, v235, v236
	v_cvt_pk_bf16_f32 v241, v237, v238
	global_store_dwordx2 v197, v[240:241], s[4:5] offset:32
	s_nop 0
	v_mul_f32_e32 v235, v12, v33
	v_mul_f32_e32 v236, v13, v33
	v_mul_f32_e32 v237, v14, v33
	v_mul_f32_e32 v238, v15, v33
	v_cvt_pk_bf16_f32 v240, v235, v236
	v_cvt_pk_bf16_f32 v241, v237, v238
	global_store_dwordx2 v197, v[240:241], s[4:5] offset:48
	s_nop 0
	v_mul_f32_e32 v235, v16, v33
	v_mul_f32_e32 v236, v17, v33
	v_mul_f32_e32 v237, v18, v33
	v_mul_f32_e32 v238, v19, v33
	v_cvt_pk_bf16_f32 v240, v235, v236
	v_cvt_pk_bf16_f32 v241, v237, v238
	global_store_dwordx2 v197, v[240:241], s[4:5] offset:64
	s_nop 0
	v_mul_f32_e32 v235, v20, v33
	v_mul_f32_e32 v236, v21, v33
	v_mul_f32_e32 v237, v22, v33
	v_mul_f32_e32 v238, v23, v33
	v_cvt_pk_bf16_f32 v240, v235, v236
	v_cvt_pk_bf16_f32 v241, v237, v238
	global_store_dwordx2 v197, v[240:241], s[4:5] offset:80
	s_nop 0
	v_mul_f32_e32 v235, v24, v33
	v_mul_f32_e32 v236, v25, v33
	v_mul_f32_e32 v237, v26, v33
	v_mul_f32_e32 v238, v27, v33
	v_cvt_pk_bf16_f32 v240, v235, v236
	v_cvt_pk_bf16_f32 v241, v237, v238
	global_store_dwordx2 v197, v[240:241], s[4:5] offset:96
	s_nop 0
	v_mul_f32_e32 v235, v28, v33
	v_mul_f32_e32 v236, v29, v33
	v_mul_f32_e32 v237, v30, v33
	v_mul_f32_e32 v238, v31, v33
	v_cvt_pk_bf16_f32 v240, v235, v236
	v_cvt_pk_bf16_f32 v241, v237, v238
	global_store_dwordx2 v197, v[240:241], s[4:5] offset:112
	s_nop 0
	s_add_u32 s1, s1, 1
	s_cmp_lt_u32 s1, 2
	s_cbranch_scc1 .Lat_unit
	s_add_u32 s0, s0, s84
	s_branch .Lat_item
